# GLU epilogue: residual/gate loads of a 16-row group issued together with counted waits instead of one dependent round trip per column block
# speedup vs baseline: 1.0702x; 1.0013x over previous
.LBB0_803:
	s_lshl_b32 s2, s0, 8
	v_add_u32_e32 v138, s2, v143
	v_lshl_or_b32 v136, s10, 8, v145
	v_ashrrev_i32_e32 v139, 31, v138
	v_ashrrev_i32_e32 v137, 31, v136
	v_lshlrev_b64 v[140:141], 10, v[138:139]
	v_lshl_add_u64 v[140:141], v[140:141], 0, v[136:137]
	v_readlane_b32 s0, v251, 20
	v_readlane_b32 s26, v251, 24
	v_lshlrev_b64 v[140:141], 1, v[140:141]
	v_readlane_b32 s1, v251, 21
	v_readlane_b32 s27, v251, 25
	v_mul_f32_e32 v126, 0xbfb8aa3b, v126
	v_lshl_add_u64 v[148:149], s[0:1], 0, v[140:141]
	v_lshl_add_u64 v[152:153], s[26:27], 0, v[140:141]
	v_mov_b32_e32 v176, v140
	v_mov_b32_e32 v177, v141
	v_mov_b32_e32 v178, s0
	v_mov_b32_e32 v179, s1
	v_mov_b32_e32 v180, s26
	v_mov_b32_e32 v181, s27
	global_load_dwordx2 v[150:151], v[148:149], off
	v_exp_f32_e32 v126, v126
	global_load_dwordx2 v[152:153], v[152:153], off
	s_mov_b64 s[100:101], 0x20
	v_lshl_add_u64 v[182:183], v[176:177], 0, s[100:101]
	v_lshl_add_u64 v[184:185], v[178:179], 0, v[182:183]
	global_load_dwordx2 v[186:187], v[184:185], off
	v_lshl_add_u64 v[184:185], v[180:181], 0, v[182:183]
	global_load_dwordx2 v[188:189], v[184:185], off
	s_mov_b64 s[100:101], 0x100
	v_lshl_add_u64 v[182:183], v[176:177], 0, s[100:101]
	v_lshl_add_u64 v[184:185], v[178:179], 0, v[182:183]
	global_load_dwordx2 v[190:191], v[184:185], off
	v_lshl_add_u64 v[184:185], v[180:181], 0, v[182:183]
	global_load_dwordx2 v[192:193], v[184:185], off
	s_mov_b64 s[100:101], 0x120
	v_lshl_add_u64 v[182:183], v[176:177], 0, s[100:101]
	v_lshl_add_u64 v[184:185], v[178:179], 0, v[182:183]
	global_load_dwordx2 v[194:195], v[184:185], off
	v_lshl_add_u64 v[184:185], v[180:181], 0, v[182:183]
	global_load_dwordx2 v[196:197], v[184:185], off
	v_mul_f32_e32 v127, 0xbfb8aa3b, v127
	v_exp_f32_e32 v127, v127
	v_mul_f32_e32 v128, 0xbfb8aa3b, v128
	v_exp_f32_e32 v128, v128
	v_mul_f32_e32 v129, 0xbfb8aa3b, v129
	v_exp_f32_e32 v129, v129
	v_add_f32_e32 v126, 1.0, v126
	v_rcp_f32_e32 v126, v126
	v_add_f32_e32 v127, 1.0, v127
	v_rcp_f32_e32 v127, v127
	v_add_f32_e32 v128, 1.0, v128
	v_rcp_f32_e32 v128, v128
	v_add_f32_e32 v129, 1.0, v129
	v_rcp_f32_e32 v129, v129
	v_mul_f32_e32 v122, 0xbfb8aa3b, v122
	v_exp_f32_e32 v122, v122
	v_mul_f32_e32 v123, 0xbfb8aa3b, v123
	v_exp_f32_e32 v123, v123
	v_mul_f32_e32 v124, 0xbfb8aa3b, v124
	v_exp_f32_e32 v124, v124
	v_mul_f32_e32 v125, 0xbfb8aa3b, v125
	v_exp_f32_e32 v125, v125
	v_add_f32_e32 v122, 1.0, v122
	v_rcp_f32_e32 v122, v122
	v_add_f32_e32 v123, 1.0, v123
	v_rcp_f32_e32 v123, v123
	v_add_f32_e32 v124, 1.0, v124
	v_rcp_f32_e32 v124, v124
	v_add_f32_e32 v125, 1.0, v125
	v_rcp_f32_e32 v125, v125
	v_mul_f32_e32 v118, 0xbfb8aa3b, v118
	v_exp_f32_e32 v118, v118
	v_mul_f32_e32 v119, 0xbfb8aa3b, v119
	v_exp_f32_e32 v119, v119
	v_mul_f32_e32 v120, 0xbfb8aa3b, v120
	v_exp_f32_e32 v120, v120
	v_mul_f32_e32 v121, 0xbfb8aa3b, v121
	v_exp_f32_e32 v121, v121
	v_add_f32_e32 v118, 1.0, v118
	v_rcp_f32_e32 v118, v118
	v_add_f32_e32 v119, 1.0, v119
	v_rcp_f32_e32 v119, v119
	v_add_f32_e32 v120, 1.0, v120
	v_rcp_f32_e32 v120, v120
	v_add_f32_e32 v121, 1.0, v121
	v_rcp_f32_e32 v121, v121
	v_mul_f32_e32 v114, 0xbfb8aa3b, v114
	v_exp_f32_e32 v114, v114
	v_mul_f32_e32 v115, 0xbfb8aa3b, v115
	v_exp_f32_e32 v115, v115
	v_mul_f32_e32 v116, 0xbfb8aa3b, v116
	v_exp_f32_e32 v116, v116
	v_mul_f32_e32 v117, 0xbfb8aa3b, v117
	v_exp_f32_e32 v117, v117
	v_add_f32_e32 v114, 1.0, v114
	v_rcp_f32_e32 v114, v114
	v_add_f32_e32 v115, 1.0, v115
	v_rcp_f32_e32 v115, v115
	v_add_f32_e32 v116, 1.0, v116
	v_rcp_f32_e32 v116, v116
	v_add_f32_e32 v117, 1.0, v117
	v_rcp_f32_e32 v117, v117
	s_waitcnt vmcnt(6)
	v_lshlrev_b32_e32 v154, 16, v150
	v_lshlrev_b32_e32 v155, 16, v152
	v_fmac_f32_e32 v154, v126, v155
	v_and_b32_e32 v126, 0xffff0000, v150
	v_and_b32_e32 v150, 0xffff0000, v152
	v_fmac_f32_e32 v126, v127, v150
	v_lshlrev_b32_e32 v127, 16, v151
	v_lshlrev_b32_e32 v150, 16, v153
	v_fmac_f32_e32 v127, v128, v150
	v_and_b32_e32 v128, 0xffff0000, v151
	v_and_b32_e32 v150, 0xffff0000, v153
	v_fmac_f32_e32 v128, v129, v150
	v_cvt_pk_bf16_f32 v126, v154, v126
	v_cvt_pk_bf16_f32 v127, v127, v128
	global_store_dwordx2 v[148:149], v[126:127], off
	v_lshlrev_b32_e32 v128, 16, v126
	v_and_b32_e32 v126, 0xffff0000, v126
	v_lshlrev_b32_e32 v129, 16, v127
	v_and_b32_e32 v127, 0xffff0000, v127
	v_mul_f32_e32 v126, v126, v126
	v_mul_f32_e32 v127, v127, v127
	v_fmac_f32_e32 v126, v128, v128
	v_fmac_f32_e32 v127, v129, v129
	v_add_f32_e32 v150, v126, v127
	v_or_b32_e32 v126, 32, v140
	v_mov_b32_e32 v127, v141
	v_lshl_add_u64 v[128:129], s[0:1], 0, v[126:127]
	v_lshl_add_u64 v[126:127], s[26:27], 0, v[126:127]
	s_nop 0
	s_waitcnt vmcnt(5)
	v_mov_b32_e32 v148, v186
	v_mov_b32_e32 v149, v187
	v_mov_b32_e32 v126, v188
	v_mov_b32_e32 v127, v189
	v_lshlrev_b32_e32 v151, 16, v148
	v_lshlrev_b32_e32 v152, 16, v126
	v_fmac_f32_e32 v151, v122, v152
	v_and_b32_e32 v122, 0xffff0000, v148
	v_and_b32_e32 v126, 0xffff0000, v126
	v_fmac_f32_e32 v122, v123, v126
	v_lshlrev_b32_e32 v123, 16, v149
	v_lshlrev_b32_e32 v126, 16, v127
	v_fmac_f32_e32 v123, v124, v126
	v_and_b32_e32 v124, 0xffff0000, v149
	v_and_b32_e32 v126, 0xffff0000, v127
	v_fmac_f32_e32 v124, v125, v126
	v_cvt_pk_bf16_f32 v122, v151, v122
	v_cvt_pk_bf16_f32 v123, v123, v124
	global_store_dwordx2 v[128:129], v[122:123], off
	v_lshlrev_b32_e32 v124, 16, v122
	v_and_b32_e32 v122, 0xffff0000, v122
	v_lshlrev_b32_e32 v125, 16, v123
	v_and_b32_e32 v123, 0xffff0000, v123
	v_mul_f32_e32 v122, v122, v122
	v_mul_f32_e32 v123, v123, v123
	v_fmac_f32_e32 v122, v124, v124
	v_fmac_f32_e32 v123, v125, v125
	v_add_f32_e32 v122, v122, v123
	v_add_f32_e32 v128, v150, v122
	v_or_b32_e32 v122, 0x100, v140
	v_mov_b32_e32 v123, v141
	v_lshl_add_u64 v[124:125], s[0:1], 0, v[122:123]
	v_lshl_add_u64 v[122:123], s[26:27], 0, v[122:123]
	v_or_b32_e32 v140, 0x120, v140
	s_waitcnt vmcnt(4)
	v_mov_b32_e32 v126, v190
	v_mov_b32_e32 v127, v191
	v_mov_b32_e32 v122, v192
	v_mov_b32_e32 v123, v193
	v_lshlrev_b32_e32 v129, 16, v126
	v_lshlrev_b32_e32 v148, 16, v122
	v_fmac_f32_e32 v129, v118, v148
	v_and_b32_e32 v118, 0xffff0000, v126
	v_and_b32_e32 v122, 0xffff0000, v122
	v_fmac_f32_e32 v118, v119, v122
	v_lshlrev_b32_e32 v119, 16, v127
	v_lshlrev_b32_e32 v122, 16, v123
	v_fmac_f32_e32 v119, v120, v122
	v_and_b32_e32 v120, 0xffff0000, v127
	v_and_b32_e32 v122, 0xffff0000, v123
	v_fmac_f32_e32 v120, v121, v122
	v_cvt_pk_bf16_f32 v118, v129, v118
	v_cvt_pk_bf16_f32 v119, v119, v120
	global_store_dwordx2 v[124:125], v[118:119], off
	v_lshlrev_b32_e32 v120, 16, v118
	v_and_b32_e32 v118, 0xffff0000, v118
	v_lshlrev_b32_e32 v121, 16, v119
	v_and_b32_e32 v119, 0xffff0000, v119
	v_mul_f32_e32 v118, v118, v118
	v_mul_f32_e32 v119, v119, v119
	v_fmac_f32_e32 v118, v120, v120
	v_fmac_f32_e32 v119, v121, v121
	v_add_f32_e32 v118, v118, v119
	v_add_f32_e32 v124, v128, v118
	v_lshl_add_u64 v[118:119], s[0:1], 0, v[140:141]
	v_lshl_add_u64 v[122:123], s[26:27], 0, v[140:141]
	s_nop 0
	s_waitcnt vmcnt(3)
	v_mov_b32_e32 v120, v194
	v_mov_b32_e32 v121, v195
	v_mov_b32_e32 v122, v196
	v_mov_b32_e32 v123, v197
	v_lshlrev_b32_e32 v125, 16, v120
	v_lshlrev_b32_e32 v126, 16, v122
	v_fmac_f32_e32 v125, v114, v126
	v_and_b32_e32 v114, 0xffff0000, v120
	v_and_b32_e32 v120, 0xffff0000, v122
	v_fmac_f32_e32 v114, v115, v120
	v_lshlrev_b32_e32 v115, 16, v121
	v_lshlrev_b32_e32 v120, 16, v123
	v_fmac_f32_e32 v115, v116, v120
	v_and_b32_e32 v116, 0xffff0000, v121
	v_and_b32_e32 v120, 0xffff0000, v123
	v_fmac_f32_e32 v116, v117, v120
	v_cvt_pk_bf16_f32 v114, v125, v114
	v_cvt_pk_bf16_f32 v115, v115, v116
	global_store_dwordx2 v[118:119], v[114:115], off
	v_lshlrev_b32_e32 v116, 16, v114
	v_and_b32_e32 v114, 0xffff0000, v114
	v_lshlrev_b32_e32 v117, 16, v115
	v_and_b32_e32 v115, 0xffff0000, v115
	v_mul_f32_e32 v114, v114, v114
	v_mul_f32_e32 v115, v115, v115
	v_fmac_f32_e32 v114, v116, v116
	v_fmac_f32_e32 v115, v117, v117
	v_and_b32_e32 v116, 64, v209
	v_add_f32_e32 v114, v114, v115
	v_xor_b32_e32 v115, 16, v209
	v_add_u32_e32 v117, 64, v116
	v_cmp_lt_i32_e32 vcc, v115, v117
	v_add_f32_e32 v114, v124, v114
	s_nop 0
	v_cndmask_b32_e32 v115, v209, v115, vcc
	v_lshlrev_b32_e32 v116, 2, v115
	ds_bpermute_b32 v115, v116, v114
	s_waitcnt lgkmcnt(0)
	v_add_f32_e32 v114, v114, v115
	v_xor_b32_e32 v115, 32, v209
	v_cmp_lt_i32_e32 vcc, v115, v117
	s_nop 1
	v_cndmask_b32_e32 v115, v209, v115, vcc
	v_lshlrev_b32_e32 v117, 2, v115
	ds_bpermute_b32 v115, v117, v114
	s_and_saveexec_b64 s[0:1], s[4:5]
	s_cbranch_execz .LBB0_805
	s_waitcnt lgkmcnt(0)
	v_add_f32_e32 v114, v114, v115
	ds_write_b32 v146, v114
.LBB0_805:
	s_or_b64 exec, exec, s[0:1]
	v_or_b32_e32 v114, 16, v138
	s_waitcnt lgkmcnt(0)
	v_ashrrev_i32_e32 v115, 31, v114
	v_lshlrev_b64 v[114:115], 10, v[114:115]
	v_lshl_add_u64 v[114:115], v[114:115], 0, v[136:137]
	v_readlane_b32 s0, v251, 20
	v_readlane_b32 s26, v251, 24
	v_lshlrev_b64 v[114:115], 1, v[114:115]
	v_readlane_b32 s1, v251, 21
	v_readlane_b32 s27, v251, 25
	v_mul_f32_e32 v110, 0xbfb8aa3b, v110
	v_lshl_add_u64 v[118:119], s[0:1], 0, v[114:115]
	v_lshl_add_u64 v[122:123], s[26:27], 0, v[114:115]
	global_load_dwordx2 v[120:121], v[118:119], off
	v_exp_f32_e32 v110, v110
	global_load_dwordx2 v[122:123], v[122:123], off
	s_mov_b64 s[100:101], 0x8020
	v_lshl_add_u64 v[182:183], v[176:177], 0, s[100:101]
	v_lshl_add_u64 v[184:185], v[178:179], 0, v[182:183]
	global_load_dwordx2 v[186:187], v[184:185], off
	v_lshl_add_u64 v[184:185], v[180:181], 0, v[182:183]
	global_load_dwordx2 v[188:189], v[184:185], off
	s_mov_b64 s[100:101], 0x8100
	v_lshl_add_u64 v[182:183], v[176:177], 0, s[100:101]
	v_lshl_add_u64 v[184:185], v[178:179], 0, v[182:183]
	global_load_dwordx2 v[190:191], v[184:185], off
	v_lshl_add_u64 v[184:185], v[180:181], 0, v[182:183]
	global_load_dwordx2 v[192:193], v[184:185], off
	s_mov_b64 s[100:101], 0x8120
	v_lshl_add_u64 v[182:183], v[176:177], 0, s[100:101]
	v_lshl_add_u64 v[184:185], v[178:179], 0, v[182:183]
	global_load_dwordx2 v[194:195], v[184:185], off
	v_lshl_add_u64 v[184:185], v[180:181], 0, v[182:183]
	global_load_dwordx2 v[196:197], v[184:185], off
	v_mul_f32_e32 v111, 0xbfb8aa3b, v111
	v_exp_f32_e32 v111, v111
	v_mul_f32_e32 v112, 0xbfb8aa3b, v112
	v_exp_f32_e32 v112, v112
	v_mul_f32_e32 v113, 0xbfb8aa3b, v113
	v_exp_f32_e32 v113, v113
	v_add_f32_e32 v110, 1.0, v110
	v_rcp_f32_e32 v110, v110
	v_add_f32_e32 v111, 1.0, v111
	v_rcp_f32_e32 v111, v111
	v_add_f32_e32 v112, 1.0, v112
	v_rcp_f32_e32 v112, v112
	v_add_f32_e32 v113, 1.0, v113
	v_rcp_f32_e32 v113, v113
	v_mul_f32_e32 v106, 0xbfb8aa3b, v106
	v_exp_f32_e32 v106, v106
	v_mul_f32_e32 v107, 0xbfb8aa3b, v107
	v_exp_f32_e32 v107, v107
	v_mul_f32_e32 v108, 0xbfb8aa3b, v108
	v_exp_f32_e32 v108, v108
	v_mul_f32_e32 v109, 0xbfb8aa3b, v109
	v_exp_f32_e32 v109, v109
	v_add_f32_e32 v106, 1.0, v106
	v_rcp_f32_e32 v106, v106
	v_add_f32_e32 v107, 1.0, v107
	v_rcp_f32_e32 v107, v107
	v_add_f32_e32 v108, 1.0, v108
	v_rcp_f32_e32 v108, v108
	v_add_f32_e32 v109, 1.0, v109
	v_rcp_f32_e32 v109, v109
	v_mul_f32_e32 v102, 0xbfb8aa3b, v102
	v_exp_f32_e32 v102, v102
	v_mul_f32_e32 v103, 0xbfb8aa3b, v103
	v_exp_f32_e32 v103, v103
	v_mul_f32_e32 v104, 0xbfb8aa3b, v104
	v_exp_f32_e32 v104, v104
	v_mul_f32_e32 v105, 0xbfb8aa3b, v105
	v_exp_f32_e32 v105, v105
	v_add_f32_e32 v102, 1.0, v102
	v_rcp_f32_e32 v102, v102
	v_add_f32_e32 v103, 1.0, v103
	v_rcp_f32_e32 v103, v103
	v_add_f32_e32 v104, 1.0, v104
	v_rcp_f32_e32 v104, v104
	v_add_f32_e32 v105, 1.0, v105
	v_rcp_f32_e32 v105, v105
	v_mul_f32_e32 v98, 0xbfb8aa3b, v98
	v_exp_f32_e32 v98, v98
	v_mul_f32_e32 v99, 0xbfb8aa3b, v99
	v_exp_f32_e32 v99, v99
	v_mul_f32_e32 v100, 0xbfb8aa3b, v100
	v_exp_f32_e32 v100, v100
	v_mul_f32_e32 v101, 0xbfb8aa3b, v101
	v_exp_f32_e32 v101, v101
	v_add_f32_e32 v98, 1.0, v98
	v_rcp_f32_e32 v98, v98
	v_add_f32_e32 v99, 1.0, v99
	v_rcp_f32_e32 v99, v99
	v_add_f32_e32 v100, 1.0, v100
	v_rcp_f32_e32 v100, v100
	v_add_f32_e32 v101, 1.0, v101
	v_rcp_f32_e32 v101, v101
	s_waitcnt vmcnt(7)
	v_lshlrev_b32_e32 v124, 16, v120
	s_waitcnt vmcnt(6)
	v_lshlrev_b32_e32 v125, 16, v122
	v_fmac_f32_e32 v124, v110, v125
	v_and_b32_e32 v110, 0xffff0000, v120
	v_and_b32_e32 v120, 0xffff0000, v122
	v_fmac_f32_e32 v110, v111, v120
	v_lshlrev_b32_e32 v111, 16, v121
	v_lshlrev_b32_e32 v120, 16, v123
	v_fmac_f32_e32 v111, v112, v120
	v_and_b32_e32 v112, 0xffff0000, v121
	v_and_b32_e32 v120, 0xffff0000, v123
	v_fmac_f32_e32 v112, v113, v120
	v_cvt_pk_bf16_f32 v110, v124, v110
	v_cvt_pk_bf16_f32 v111, v111, v112
	global_store_dwordx2 v[118:119], v[110:111], off
	v_lshlrev_b32_e32 v112, 16, v110
	v_and_b32_e32 v110, 0xffff0000, v110
	v_lshlrev_b32_e32 v113, 16, v111
	v_and_b32_e32 v111, 0xffff0000, v111
	v_mul_f32_e32 v110, v110, v110
	v_mul_f32_e32 v111, v111, v111
	v_fmac_f32_e32 v110, v112, v112
	v_fmac_f32_e32 v111, v113, v113
	v_add_f32_e32 v120, v110, v111
	v_or_b32_e32 v110, 32, v114
	v_mov_b32_e32 v111, v115
	v_lshl_add_u64 v[112:113], s[0:1], 0, v[110:111]
	v_lshl_add_u64 v[110:111], s[26:27], 0, v[110:111]
	s_nop 0
	s_waitcnt vmcnt(5)
	v_mov_b32_e32 v118, v186
	v_mov_b32_e32 v119, v187
	v_mov_b32_e32 v110, v188
	v_mov_b32_e32 v111, v189
	v_lshlrev_b32_e32 v121, 16, v118
	v_lshlrev_b32_e32 v122, 16, v110
	v_fmac_f32_e32 v121, v106, v122
	v_and_b32_e32 v106, 0xffff0000, v118
	v_and_b32_e32 v110, 0xffff0000, v110
	v_fmac_f32_e32 v106, v107, v110
	v_lshlrev_b32_e32 v107, 16, v119
	v_lshlrev_b32_e32 v110, 16, v111
	v_fmac_f32_e32 v107, v108, v110
	v_and_b32_e32 v108, 0xffff0000, v119
	v_and_b32_e32 v110, 0xffff0000, v111
	v_fmac_f32_e32 v108, v109, v110
	v_cvt_pk_bf16_f32 v106, v121, v106
	v_cvt_pk_bf16_f32 v107, v107, v108
	global_store_dwordx2 v[112:113], v[106:107], off
	v_lshlrev_b32_e32 v108, 16, v106
	v_and_b32_e32 v106, 0xffff0000, v106
	v_lshlrev_b32_e32 v109, 16, v107
	v_and_b32_e32 v107, 0xffff0000, v107
	v_mul_f32_e32 v106, v106, v106
	v_mul_f32_e32 v107, v107, v107
	v_fmac_f32_e32 v106, v108, v108
	v_fmac_f32_e32 v107, v109, v109
	v_add_f32_e32 v106, v106, v107
	v_add_f32_e32 v112, v120, v106
	v_or_b32_e32 v106, 0x100, v114
	v_mov_b32_e32 v107, v115
	v_lshl_add_u64 v[108:109], s[0:1], 0, v[106:107]
	v_lshl_add_u64 v[106:107], s[26:27], 0, v[106:107]
	v_or_b32_e32 v114, 0x120, v114
	s_waitcnt vmcnt(4)
	v_mov_b32_e32 v110, v190
	v_mov_b32_e32 v111, v191
	v_mov_b32_e32 v106, v192
	v_mov_b32_e32 v107, v193
	v_lshlrev_b32_e32 v113, 16, v110
	v_lshlrev_b32_e32 v118, 16, v106
	v_fmac_f32_e32 v113, v102, v118
	v_and_b32_e32 v102, 0xffff0000, v110
	v_and_b32_e32 v106, 0xffff0000, v106
	v_fmac_f32_e32 v102, v103, v106
	v_lshlrev_b32_e32 v103, 16, v111
	v_lshlrev_b32_e32 v106, 16, v107
	v_fmac_f32_e32 v103, v104, v106
	v_and_b32_e32 v104, 0xffff0000, v111
	v_and_b32_e32 v106, 0xffff0000, v107
	v_fmac_f32_e32 v104, v105, v106
	v_cvt_pk_bf16_f32 v102, v113, v102
	v_cvt_pk_bf16_f32 v103, v103, v104
	global_store_dwordx2 v[108:109], v[102:103], off
	v_lshlrev_b32_e32 v104, 16, v102
	v_and_b32_e32 v102, 0xffff0000, v102
	v_lshlrev_b32_e32 v105, 16, v103
	v_and_b32_e32 v103, 0xffff0000, v103
	v_mul_f32_e32 v102, v102, v102
	v_mul_f32_e32 v103, v103, v103
	v_fmac_f32_e32 v102, v104, v104
	v_fmac_f32_e32 v103, v105, v105
	v_add_f32_e32 v102, v102, v103
	v_add_f32_e32 v108, v112, v102
	v_lshl_add_u64 v[102:103], s[0:1], 0, v[114:115]
	v_lshl_add_u64 v[106:107], s[26:27], 0, v[114:115]
	s_nop 0
	s_waitcnt vmcnt(3)
	v_mov_b32_e32 v104, v194
	v_mov_b32_e32 v105, v195
	v_mov_b32_e32 v106, v196
	v_mov_b32_e32 v107, v197
	v_lshlrev_b32_e32 v109, 16, v104
	v_lshlrev_b32_e32 v110, 16, v106
	v_fmac_f32_e32 v109, v98, v110
	v_and_b32_e32 v98, 0xffff0000, v104
	v_and_b32_e32 v104, 0xffff0000, v106
	v_fmac_f32_e32 v98, v99, v104
	v_lshlrev_b32_e32 v99, 16, v105
	v_lshlrev_b32_e32 v104, 16, v107
	v_fmac_f32_e32 v99, v100, v104
	v_and_b32_e32 v100, 0xffff0000, v105
	v_and_b32_e32 v104, 0xffff0000, v107
	v_fmac_f32_e32 v100, v101, v104
	v_cvt_pk_bf16_f32 v98, v109, v98
	v_cvt_pk_bf16_f32 v99, v99, v100
	global_store_dwordx2 v[102:103], v[98:99], off
	v_lshlrev_b32_e32 v100, 16, v98
	v_and_b32_e32 v98, 0xffff0000, v98
	v_lshlrev_b32_e32 v101, 16, v99
	v_and_b32_e32 v99, 0xffff0000, v99
	v_mul_f32_e32 v98, v98, v98
	v_mul_f32_e32 v99, v99, v99
	v_fmac_f32_e32 v98, v100, v100
	v_fmac_f32_e32 v99, v101, v101
	v_add_f32_e32 v98, v98, v99
	v_add_f32_e32 v98, v108, v98
	ds_bpermute_b32 v99, v116, v98
	s_waitcnt lgkmcnt(0)
	v_add_f32_e32 v98, v98, v99
	ds_bpermute_b32 v99, v117, v98
	s_and_saveexec_b64 s[0:1], s[4:5]
	s_cbranch_execz .LBB0_807
	s_waitcnt lgkmcnt(0)
	v_add_f32_e32 v98, v98, v99
	ds_write_b32 v146, v98 offset:256
.LBB0_807:
	s_or_b64 exec, exec, s[0:1]
	v_or_b32_e32 v98, 32, v138
	s_waitcnt lgkmcnt(0)
	v_ashrrev_i32_e32 v99, 31, v98
	v_lshlrev_b64 v[98:99], 10, v[98:99]
	v_lshl_add_u64 v[98:99], v[98:99], 0, v[136:137]
	v_readlane_b32 s0, v251, 20
	v_readlane_b32 s26, v251, 24
	v_lshlrev_b64 v[98:99], 1, v[98:99]
	v_readlane_b32 s1, v251, 21
	v_readlane_b32 s27, v251, 25
	v_mul_f32_e32 v92, 0xbfb8aa3b, v92
	v_lshl_add_u64 v[100:101], s[0:1], 0, v[98:99]
	v_lshl_add_u64 v[104:105], s[26:27], 0, v[98:99]
	global_load_dwordx2 v[102:103], v[100:101], off
	v_exp_f32_e32 v92, v92
	global_load_dwordx2 v[104:105], v[104:105], off
	s_mov_b64 s[100:101], 0x10020
	v_lshl_add_u64 v[182:183], v[176:177], 0, s[100:101]
	v_lshl_add_u64 v[184:185], v[178:179], 0, v[182:183]
	global_load_dwordx2 v[186:187], v[184:185], off
	v_lshl_add_u64 v[184:185], v[180:181], 0, v[182:183]
	global_load_dwordx2 v[188:189], v[184:185], off
	s_mov_b64 s[100:101], 0x10100
	v_lshl_add_u64 v[182:183], v[176:177], 0, s[100:101]
	v_lshl_add_u64 v[184:185], v[178:179], 0, v[182:183]
	global_load_dwordx2 v[190:191], v[184:185], off
	v_lshl_add_u64 v[184:185], v[180:181], 0, v[182:183]
	global_load_dwordx2 v[192:193], v[184:185], off
	s_mov_b64 s[100:101], 0x10120
	v_lshl_add_u64 v[182:183], v[176:177], 0, s[100:101]
	v_lshl_add_u64 v[184:185], v[178:179], 0, v[182:183]
	global_load_dwordx2 v[194:195], v[184:185], off
	v_lshl_add_u64 v[184:185], v[180:181], 0, v[182:183]
	global_load_dwordx2 v[196:197], v[184:185], off
	v_mul_f32_e32 v93, 0xbfb8aa3b, v93
	v_exp_f32_e32 v93, v93
	v_mul_f32_e32 v94, 0xbfb8aa3b, v94
	v_exp_f32_e32 v94, v94
	v_mul_f32_e32 v95, 0xbfb8aa3b, v95
	v_exp_f32_e32 v95, v95
	v_add_f32_e32 v92, 1.0, v92
	v_rcp_f32_e32 v92, v92
	v_add_f32_e32 v93, 1.0, v93
	v_rcp_f32_e32 v93, v93
	v_add_f32_e32 v94, 1.0, v94
	v_rcp_f32_e32 v94, v94
	v_add_f32_e32 v95, 1.0, v95
	v_rcp_f32_e32 v95, v95
	v_mul_f32_e32 v88, 0xbfb8aa3b, v88
	v_exp_f32_e32 v88, v88
	v_mul_f32_e32 v89, 0xbfb8aa3b, v89
	v_exp_f32_e32 v89, v89
	v_mul_f32_e32 v90, 0xbfb8aa3b, v90
	v_exp_f32_e32 v90, v90
	v_mul_f32_e32 v91, 0xbfb8aa3b, v91
	v_exp_f32_e32 v91, v91
	v_add_f32_e32 v88, 1.0, v88
	v_rcp_f32_e32 v88, v88
	v_add_f32_e32 v89, 1.0, v89
	v_rcp_f32_e32 v89, v89
	v_add_f32_e32 v90, 1.0, v90
	v_rcp_f32_e32 v90, v90
	v_add_f32_e32 v91, 1.0, v91
	v_rcp_f32_e32 v91, v91
	v_mul_f32_e32 v84, 0xbfb8aa3b, v84
	v_exp_f32_e32 v84, v84
	v_mul_f32_e32 v85, 0xbfb8aa3b, v85
	v_exp_f32_e32 v85, v85
	v_mul_f32_e32 v86, 0xbfb8aa3b, v86
	v_exp_f32_e32 v86, v86
	v_mul_f32_e32 v87, 0xbfb8aa3b, v87
	v_exp_f32_e32 v87, v87
	v_add_f32_e32 v84, 1.0, v84
	v_rcp_f32_e32 v84, v84
	v_add_f32_e32 v85, 1.0, v85
	v_rcp_f32_e32 v85, v85
	v_add_f32_e32 v86, 1.0, v86
	v_rcp_f32_e32 v86, v86
	v_add_f32_e32 v87, 1.0, v87
	v_rcp_f32_e32 v87, v87
	v_mul_f32_e32 v80, 0xbfb8aa3b, v80
	v_exp_f32_e32 v80, v80
	v_mul_f32_e32 v81, 0xbfb8aa3b, v81
	v_exp_f32_e32 v81, v81
	v_mul_f32_e32 v82, 0xbfb8aa3b, v82
	v_exp_f32_e32 v82, v82
	v_mul_f32_e32 v83, 0xbfb8aa3b, v83
	v_exp_f32_e32 v83, v83
	v_add_f32_e32 v80, 1.0, v80
	v_rcp_f32_e32 v80, v80
	v_add_f32_e32 v81, 1.0, v81
	v_rcp_f32_e32 v81, v81
	v_add_f32_e32 v82, 1.0, v82
	v_rcp_f32_e32 v82, v82
	v_add_f32_e32 v83, 1.0, v83
	v_rcp_f32_e32 v83, v83
	s_waitcnt vmcnt(7)
	v_lshlrev_b32_e32 v106, 16, v102
	s_waitcnt vmcnt(6)
	v_lshlrev_b32_e32 v107, 16, v104
	v_fmac_f32_e32 v106, v92, v107
	v_and_b32_e32 v92, 0xffff0000, v102
	v_and_b32_e32 v102, 0xffff0000, v104
	v_fmac_f32_e32 v92, v93, v102
	v_lshlrev_b32_e32 v93, 16, v103
	v_lshlrev_b32_e32 v102, 16, v105
	v_fmac_f32_e32 v93, v94, v102
	v_and_b32_e32 v94, 0xffff0000, v103
	v_and_b32_e32 v102, 0xffff0000, v105
	v_fmac_f32_e32 v94, v95, v102
	v_cvt_pk_bf16_f32 v92, v106, v92
	v_cvt_pk_bf16_f32 v93, v93, v94
	global_store_dwordx2 v[100:101], v[92:93], off
	v_lshlrev_b32_e32 v94, 16, v92
	v_and_b32_e32 v92, 0xffff0000, v92
	v_lshlrev_b32_e32 v95, 16, v93
	v_and_b32_e32 v93, 0xffff0000, v93
	v_mul_f32_e32 v92, v92, v92
	v_mul_f32_e32 v93, v93, v93
	v_fmac_f32_e32 v92, v94, v94
	v_fmac_f32_e32 v93, v95, v95
	v_add_f32_e32 v102, v92, v93
	v_or_b32_e32 v92, 32, v98
	v_mov_b32_e32 v93, v99
	v_lshl_add_u64 v[94:95], s[0:1], 0, v[92:93]
	v_lshl_add_u64 v[92:93], s[26:27], 0, v[92:93]
	s_nop 0
	s_waitcnt vmcnt(5)
	v_mov_b32_e32 v100, v186
	v_mov_b32_e32 v101, v187
	v_mov_b32_e32 v92, v188
	v_mov_b32_e32 v93, v189
	v_lshlrev_b32_e32 v103, 16, v100
	v_lshlrev_b32_e32 v104, 16, v92
	v_fmac_f32_e32 v103, v88, v104
	v_and_b32_e32 v88, 0xffff0000, v100
	v_and_b32_e32 v92, 0xffff0000, v92
	v_fmac_f32_e32 v88, v89, v92
	v_lshlrev_b32_e32 v89, 16, v101
	v_lshlrev_b32_e32 v92, 16, v93
	v_fmac_f32_e32 v89, v90, v92
	v_and_b32_e32 v90, 0xffff0000, v101
	v_and_b32_e32 v92, 0xffff0000, v93
	v_fmac_f32_e32 v90, v91, v92
	v_cvt_pk_bf16_f32 v88, v103, v88
	v_cvt_pk_bf16_f32 v89, v89, v90
	global_store_dwordx2 v[94:95], v[88:89], off
	v_lshlrev_b32_e32 v90, 16, v88
	v_and_b32_e32 v88, 0xffff0000, v88
	v_lshlrev_b32_e32 v91, 16, v89
	v_and_b32_e32 v89, 0xffff0000, v89
	v_mul_f32_e32 v88, v88, v88
	v_mul_f32_e32 v89, v89, v89
	v_fmac_f32_e32 v88, v90, v90
	v_fmac_f32_e32 v89, v91, v91
	v_add_f32_e32 v88, v88, v89
	v_add_f32_e32 v94, v102, v88
	v_or_b32_e32 v88, 0x100, v98
	v_mov_b32_e32 v89, v99
	v_lshl_add_u64 v[90:91], s[0:1], 0, v[88:89]
	v_lshl_add_u64 v[88:89], s[26:27], 0, v[88:89]
	v_or_b32_e32 v98, 0x120, v98
	s_waitcnt vmcnt(4)
	v_mov_b32_e32 v92, v190
	v_mov_b32_e32 v93, v191
	v_mov_b32_e32 v88, v192
	v_mov_b32_e32 v89, v193
	v_lshlrev_b32_e32 v95, 16, v92
	v_lshlrev_b32_e32 v100, 16, v88
	v_fmac_f32_e32 v95, v84, v100
	v_and_b32_e32 v84, 0xffff0000, v92
	v_and_b32_e32 v88, 0xffff0000, v88
	v_fmac_f32_e32 v84, v85, v88
	v_lshlrev_b32_e32 v85, 16, v93
	v_lshlrev_b32_e32 v88, 16, v89
	v_fmac_f32_e32 v85, v86, v88
	v_and_b32_e32 v86, 0xffff0000, v93
	v_and_b32_e32 v88, 0xffff0000, v89
	v_fmac_f32_e32 v86, v87, v88
	v_cvt_pk_bf16_f32 v84, v95, v84
	v_cvt_pk_bf16_f32 v85, v85, v86
	global_store_dwordx2 v[90:91], v[84:85], off
	v_lshlrev_b32_e32 v86, 16, v84
	v_and_b32_e32 v84, 0xffff0000, v84
	v_lshlrev_b32_e32 v87, 16, v85
	v_and_b32_e32 v85, 0xffff0000, v85
	v_mul_f32_e32 v84, v84, v84
	v_mul_f32_e32 v85, v85, v85
	v_fmac_f32_e32 v84, v86, v86
	v_fmac_f32_e32 v85, v87, v87
	v_add_f32_e32 v84, v84, v85
	v_add_f32_e32 v90, v94, v84
	v_lshl_add_u64 v[84:85], s[0:1], 0, v[98:99]
	v_lshl_add_u64 v[88:89], s[26:27], 0, v[98:99]
	s_nop 0
	s_waitcnt vmcnt(3)
	v_mov_b32_e32 v86, v194
	v_mov_b32_e32 v87, v195
	v_mov_b32_e32 v88, v196
	v_mov_b32_e32 v89, v197
	v_lshlrev_b32_e32 v91, 16, v86
	v_lshlrev_b32_e32 v92, 16, v88
	v_fmac_f32_e32 v91, v80, v92
	v_and_b32_e32 v80, 0xffff0000, v86
	v_and_b32_e32 v86, 0xffff0000, v88
	v_fmac_f32_e32 v80, v81, v86
	v_lshlrev_b32_e32 v81, 16, v87
	v_lshlrev_b32_e32 v86, 16, v89
	v_fmac_f32_e32 v81, v82, v86
	v_and_b32_e32 v82, 0xffff0000, v87
	v_and_b32_e32 v86, 0xffff0000, v89
	v_fmac_f32_e32 v82, v83, v86
	v_cvt_pk_bf16_f32 v80, v91, v80
	v_cvt_pk_bf16_f32 v81, v81, v82
	global_store_dwordx2 v[84:85], v[80:81], off
	v_lshlrev_b32_e32 v82, 16, v80
	v_and_b32_e32 v80, 0xffff0000, v80
	v_lshlrev_b32_e32 v83, 16, v81
	v_and_b32_e32 v81, 0xffff0000, v81
	v_mul_f32_e32 v80, v80, v80
	v_mul_f32_e32 v81, v81, v81
	v_fmac_f32_e32 v80, v82, v82
	v_fmac_f32_e32 v81, v83, v83
	v_add_f32_e32 v80, v80, v81
	v_add_f32_e32 v80, v90, v80
	ds_bpermute_b32 v81, v116, v80
	s_waitcnt lgkmcnt(0)
	v_add_f32_e32 v80, v80, v81
	ds_bpermute_b32 v81, v117, v80
	s_and_saveexec_b64 s[0:1], s[4:5]
	v_readlane_b32 s48, v251, 32
	v_readlane_b32 s49, v251, 33
	s_movk_i32 s50, 0x7fff
	s_cbranch_execz .LBB0_809
	s_waitcnt lgkmcnt(0)
	v_add_f32_e32 v80, v80, v81
	ds_write_b32 v146, v80 offset:512
.LBB0_809:
	s_or_b64 exec, exec, s[0:1]
	v_or_b32_e32 v80, 48, v138
	s_waitcnt lgkmcnt(0)
	v_ashrrev_i32_e32 v81, 31, v80
	v_lshlrev_b64 v[80:81], 10, v[80:81]
	v_lshl_add_u64 v[80:81], v[80:81], 0, v[136:137]
	v_readlane_b32 s0, v251, 20
	v_readlane_b32 s26, v251, 24
	v_lshlrev_b64 v[80:81], 1, v[80:81]
	v_readlane_b32 s1, v251, 21
	v_readlane_b32 s27, v251, 25
	v_mul_f32_e32 v76, 0xbfb8aa3b, v76
	v_lshl_add_u64 v[82:83], s[0:1], 0, v[80:81]
	v_lshl_add_u64 v[86:87], s[26:27], 0, v[80:81]
	global_load_dwordx2 v[84:85], v[82:83], off
	v_exp_f32_e32 v76, v76
	global_load_dwordx2 v[86:87], v[86:87], off
	s_mov_b64 s[100:101], 0x18020
	v_lshl_add_u64 v[182:183], v[176:177], 0, s[100:101]
	v_lshl_add_u64 v[184:185], v[178:179], 0, v[182:183]
	global_load_dwordx2 v[186:187], v[184:185], off
	v_lshl_add_u64 v[184:185], v[180:181], 0, v[182:183]
	global_load_dwordx2 v[188:189], v[184:185], off
	s_mov_b64 s[100:101], 0x18100
	v_lshl_add_u64 v[182:183], v[176:177], 0, s[100:101]
	v_lshl_add_u64 v[184:185], v[178:179], 0, v[182:183]
	global_load_dwordx2 v[190:191], v[184:185], off
	v_lshl_add_u64 v[184:185], v[180:181], 0, v[182:183]
	global_load_dwordx2 v[192:193], v[184:185], off
	s_mov_b64 s[100:101], 0x18120
	v_lshl_add_u64 v[182:183], v[176:177], 0, s[100:101]
	v_lshl_add_u64 v[184:185], v[178:179], 0, v[182:183]
	global_load_dwordx2 v[194:195], v[184:185], off
	v_lshl_add_u64 v[184:185], v[180:181], 0, v[182:183]
	global_load_dwordx2 v[196:197], v[184:185], off
	v_mul_f32_e32 v77, 0xbfb8aa3b, v77
	v_exp_f32_e32 v77, v77
	v_mul_f32_e32 v78, 0xbfb8aa3b, v78
	v_exp_f32_e32 v78, v78
	v_mul_f32_e32 v79, 0xbfb8aa3b, v79
	v_exp_f32_e32 v79, v79
	v_add_f32_e32 v76, 1.0, v76
	v_rcp_f32_e32 v76, v76
	v_add_f32_e32 v77, 1.0, v77
	v_rcp_f32_e32 v77, v77
	v_add_f32_e32 v78, 1.0, v78
	v_rcp_f32_e32 v78, v78
	v_add_f32_e32 v79, 1.0, v79
	v_rcp_f32_e32 v79, v79
	v_mul_f32_e32 v72, 0xbfb8aa3b, v72
	v_exp_f32_e32 v72, v72
	v_mul_f32_e32 v73, 0xbfb8aa3b, v73
	v_exp_f32_e32 v73, v73
	v_mul_f32_e32 v74, 0xbfb8aa3b, v74
	v_exp_f32_e32 v74, v74
	v_mul_f32_e32 v75, 0xbfb8aa3b, v75
	v_exp_f32_e32 v75, v75
	v_add_f32_e32 v72, 1.0, v72
	v_rcp_f32_e32 v72, v72
	v_add_f32_e32 v73, 1.0, v73
	v_rcp_f32_e32 v73, v73
	v_add_f32_e32 v74, 1.0, v74
	v_rcp_f32_e32 v74, v74
	v_add_f32_e32 v75, 1.0, v75
	v_rcp_f32_e32 v75, v75
	v_mul_f32_e32 v68, 0xbfb8aa3b, v68
	v_exp_f32_e32 v68, v68
	v_mul_f32_e32 v69, 0xbfb8aa3b, v69
	v_exp_f32_e32 v69, v69
	v_mul_f32_e32 v70, 0xbfb8aa3b, v70
	v_exp_f32_e32 v70, v70
	v_mul_f32_e32 v71, 0xbfb8aa3b, v71
	v_exp_f32_e32 v71, v71
	v_add_f32_e32 v68, 1.0, v68
	v_rcp_f32_e32 v68, v68
	v_add_f32_e32 v69, 1.0, v69
	v_rcp_f32_e32 v69, v69
	v_add_f32_e32 v70, 1.0, v70
	v_rcp_f32_e32 v70, v70
	v_add_f32_e32 v71, 1.0, v71
	v_rcp_f32_e32 v71, v71
	v_mul_f32_e32 v64, 0xbfb8aa3b, v64
	v_exp_f32_e32 v64, v64
	v_mul_f32_e32 v65, 0xbfb8aa3b, v65
	v_exp_f32_e32 v65, v65
	v_mul_f32_e32 v66, 0xbfb8aa3b, v66
	v_exp_f32_e32 v66, v66
	v_mul_f32_e32 v67, 0xbfb8aa3b, v67
	v_exp_f32_e32 v67, v67
	v_add_f32_e32 v64, 1.0, v64
	v_rcp_f32_e32 v64, v64
	v_add_f32_e32 v65, 1.0, v65
	v_rcp_f32_e32 v65, v65
	v_add_f32_e32 v66, 1.0, v66
	v_rcp_f32_e32 v66, v66
	v_add_f32_e32 v67, 1.0, v67
	v_rcp_f32_e32 v67, v67
	s_waitcnt vmcnt(7)
	v_lshlrev_b32_e32 v88, 16, v84
	s_waitcnt vmcnt(6)
	v_lshlrev_b32_e32 v89, 16, v86
	v_fmac_f32_e32 v88, v76, v89
	v_and_b32_e32 v76, 0xffff0000, v84
	v_and_b32_e32 v84, 0xffff0000, v86
	v_fmac_f32_e32 v76, v77, v84
	v_lshlrev_b32_e32 v77, 16, v85
	v_lshlrev_b32_e32 v84, 16, v87
	v_fmac_f32_e32 v77, v78, v84
	v_and_b32_e32 v78, 0xffff0000, v85
	v_and_b32_e32 v84, 0xffff0000, v87
	v_fmac_f32_e32 v78, v79, v84
	v_cvt_pk_bf16_f32 v76, v88, v76
	v_cvt_pk_bf16_f32 v77, v77, v78
	global_store_dwordx2 v[82:83], v[76:77], off
	v_lshlrev_b32_e32 v78, 16, v76
	v_and_b32_e32 v76, 0xffff0000, v76
	v_lshlrev_b32_e32 v79, 16, v77
	v_and_b32_e32 v77, 0xffff0000, v77
	v_mul_f32_e32 v76, v76, v76
	v_mul_f32_e32 v77, v77, v77
	v_fmac_f32_e32 v76, v78, v78
	v_fmac_f32_e32 v77, v79, v79
	v_add_f32_e32 v84, v76, v77
	v_or_b32_e32 v76, 32, v80
	v_mov_b32_e32 v77, v81
	v_lshl_add_u64 v[78:79], s[0:1], 0, v[76:77]
	v_lshl_add_u64 v[76:77], s[26:27], 0, v[76:77]
	s_nop 0
	s_waitcnt vmcnt(5)
	v_mov_b32_e32 v82, v186
	v_mov_b32_e32 v83, v187
	v_mov_b32_e32 v76, v188
	v_mov_b32_e32 v77, v189
	v_lshlrev_b32_e32 v85, 16, v82
	v_lshlrev_b32_e32 v86, 16, v76
	v_fmac_f32_e32 v85, v72, v86
	v_and_b32_e32 v72, 0xffff0000, v82
	v_and_b32_e32 v76, 0xffff0000, v76
	v_fmac_f32_e32 v72, v73, v76
	v_lshlrev_b32_e32 v73, 16, v83
	v_lshlrev_b32_e32 v76, 16, v77
	v_fmac_f32_e32 v73, v74, v76
	v_and_b32_e32 v74, 0xffff0000, v83
	v_and_b32_e32 v76, 0xffff0000, v77
	v_fmac_f32_e32 v74, v75, v76
	v_cvt_pk_bf16_f32 v72, v85, v72
	v_cvt_pk_bf16_f32 v73, v73, v74
	global_store_dwordx2 v[78:79], v[72:73], off
	v_lshlrev_b32_e32 v74, 16, v72
	v_and_b32_e32 v72, 0xffff0000, v72
	v_lshlrev_b32_e32 v75, 16, v73
	v_and_b32_e32 v73, 0xffff0000, v73
	v_mul_f32_e32 v72, v72, v72
	v_mul_f32_e32 v73, v73, v73
	v_fmac_f32_e32 v72, v74, v74
	v_fmac_f32_e32 v73, v75, v75
	v_add_f32_e32 v72, v72, v73
	v_add_f32_e32 v78, v84, v72
	v_or_b32_e32 v72, 0x100, v80
	v_mov_b32_e32 v73, v81
	v_lshl_add_u64 v[74:75], s[0:1], 0, v[72:73]
	v_lshl_add_u64 v[72:73], s[26:27], 0, v[72:73]
	v_or_b32_e32 v80, 0x120, v80
	s_waitcnt vmcnt(4)
	v_mov_b32_e32 v76, v190
	v_mov_b32_e32 v77, v191
	v_mov_b32_e32 v72, v192
	v_mov_b32_e32 v73, v193
	v_lshlrev_b32_e32 v79, 16, v76
	v_lshlrev_b32_e32 v82, 16, v72
	v_fmac_f32_e32 v79, v68, v82
	v_and_b32_e32 v68, 0xffff0000, v76
	v_and_b32_e32 v72, 0xffff0000, v72
	v_fmac_f32_e32 v68, v69, v72
	v_lshlrev_b32_e32 v69, 16, v77
	v_lshlrev_b32_e32 v72, 16, v73
	v_fmac_f32_e32 v69, v70, v72
	v_and_b32_e32 v70, 0xffff0000, v77
	v_and_b32_e32 v72, 0xffff0000, v73
	v_fmac_f32_e32 v70, v71, v72
	v_cvt_pk_bf16_f32 v68, v79, v68
	v_cvt_pk_bf16_f32 v69, v69, v70
	global_store_dwordx2 v[74:75], v[68:69], off
	v_lshlrev_b32_e32 v70, 16, v68
	v_and_b32_e32 v68, 0xffff0000, v68
	v_lshlrev_b32_e32 v71, 16, v69
	v_and_b32_e32 v69, 0xffff0000, v69
	v_mul_f32_e32 v68, v68, v68
	v_mul_f32_e32 v69, v69, v69
	v_fmac_f32_e32 v68, v70, v70
	v_fmac_f32_e32 v69, v71, v71
	v_add_f32_e32 v68, v68, v69
	v_add_f32_e32 v74, v78, v68
	v_lshl_add_u64 v[68:69], s[0:1], 0, v[80:81]
	v_lshl_add_u64 v[72:73], s[26:27], 0, v[80:81]
	s_nop 0
	s_waitcnt vmcnt(3)
	v_mov_b32_e32 v70, v194
	v_mov_b32_e32 v71, v195
	v_mov_b32_e32 v72, v196
	v_mov_b32_e32 v73, v197
	v_lshlrev_b32_e32 v75, 16, v70
	v_lshlrev_b32_e32 v76, 16, v72
	v_fmac_f32_e32 v75, v64, v76
	v_and_b32_e32 v64, 0xffff0000, v70
	v_and_b32_e32 v70, 0xffff0000, v72
	v_fmac_f32_e32 v64, v65, v70
	v_lshlrev_b32_e32 v65, 16, v71
	v_lshlrev_b32_e32 v70, 16, v73
	v_fmac_f32_e32 v65, v66, v70
	v_and_b32_e32 v66, 0xffff0000, v71
	v_and_b32_e32 v70, 0xffff0000, v73
	v_fmac_f32_e32 v66, v67, v70
	v_cvt_pk_bf16_f32 v64, v75, v64
	v_cvt_pk_bf16_f32 v65, v65, v66
	global_store_dwordx2 v[68:69], v[64:65], off
	v_lshlrev_b32_e32 v66, 16, v64
	v_and_b32_e32 v64, 0xffff0000, v64
	v_lshlrev_b32_e32 v67, 16, v65
	v_and_b32_e32 v65, 0xffff0000, v65
	v_mul_f32_e32 v64, v64, v64
	v_mul_f32_e32 v65, v65, v65
	v_fmac_f32_e32 v64, v66, v66
	v_fmac_f32_e32 v65, v67, v67
	v_add_f32_e32 v64, v64, v65
	v_add_f32_e32 v64, v74, v64
	ds_bpermute_b32 v65, v116, v64
	s_waitcnt lgkmcnt(0)
	v_add_f32_e32 v64, v64, v65
	ds_bpermute_b32 v65, v117, v64
	s_and_saveexec_b64 s[0:1], s[4:5]
	s_cbranch_execz .LBB0_811
	s_waitcnt lgkmcnt(0)
	v_add_f32_e32 v64, v64, v65
	ds_write_b32 v146, v64 offset:768
.LBB0_811:
	s_or_b64 exec, exec, s[0:1]
	s_waitcnt lgkmcnt(0)
	v_lshlrev_b64 v[64:65], 10, v[138:139]
	v_lshl_add_u64 v[64:65], v[64:65], 0, v[136:137]
	v_lshlrev_b64 v[64:65], 1, v[64:65]
	s_mov_b64 s[0:1], 0x40000
	v_readlane_b32 s26, v251, 20
	v_readlane_b32 s28, v251, 24
	v_lshl_add_u64 v[66:67], v[64:65], 0, s[0:1]
	v_readlane_b32 s27, v251, 21
	v_readlane_b32 s29, v251, 25
	v_mul_f32_e32 v60, 0xbfb8aa3b, v60
	v_lshl_add_u64 v[68:69], s[26:27], 0, v[66:67]
	v_lshl_add_u64 v[66:67], s[28:29], 0, v[66:67]
	global_load_dwordx2 v[70:71], v[68:69], off
	v_exp_f32_e32 v60, v60
	global_load_dwordx2 v[66:67], v[66:67], off
	s_mov_b64 s[100:101], 0x40020
	v_lshl_add_u64 v[182:183], v[176:177], 0, s[100:101]
	v_lshl_add_u64 v[184:185], v[178:179], 0, v[182:183]
	global_load_dwordx2 v[186:187], v[184:185], off
	v_lshl_add_u64 v[184:185], v[180:181], 0, v[182:183]
	global_load_dwordx2 v[188:189], v[184:185], off
	s_mov_b64 s[100:101], 0x40100
	v_lshl_add_u64 v[182:183], v[176:177], 0, s[100:101]
	v_lshl_add_u64 v[184:185], v[178:179], 0, v[182:183]
	global_load_dwordx2 v[190:191], v[184:185], off
	v_lshl_add_u64 v[184:185], v[180:181], 0, v[182:183]
	global_load_dwordx2 v[192:193], v[184:185], off
	s_mov_b64 s[100:101], 0x40120
	v_lshl_add_u64 v[182:183], v[176:177], 0, s[100:101]
	v_lshl_add_u64 v[184:185], v[178:179], 0, v[182:183]
	global_load_dwordx2 v[194:195], v[184:185], off
	v_lshl_add_u64 v[184:185], v[180:181], 0, v[182:183]
	global_load_dwordx2 v[196:197], v[184:185], off
	v_mul_f32_e32 v61, 0xbfb8aa3b, v61
	v_exp_f32_e32 v61, v61
	v_mul_f32_e32 v62, 0xbfb8aa3b, v62
	v_exp_f32_e32 v62, v62
	v_mul_f32_e32 v63, 0xbfb8aa3b, v63
	v_exp_f32_e32 v63, v63
	v_add_f32_e32 v60, 1.0, v60
	v_rcp_f32_e32 v60, v60
	v_add_f32_e32 v61, 1.0, v61
	v_rcp_f32_e32 v61, v61
	v_add_f32_e32 v62, 1.0, v62
	v_rcp_f32_e32 v62, v62
	v_add_f32_e32 v63, 1.0, v63
	v_rcp_f32_e32 v63, v63
	s_mov_b64 s[0:1], 0x40020
	v_mul_f32_e32 v56, 0xbfb8aa3b, v56
	v_exp_f32_e32 v56, v56
	v_mul_f32_e32 v57, 0xbfb8aa3b, v57
	v_exp_f32_e32 v57, v57
	v_mul_f32_e32 v58, 0xbfb8aa3b, v58
	v_exp_f32_e32 v58, v58
	v_mul_f32_e32 v59, 0xbfb8aa3b, v59
	v_exp_f32_e32 v59, v59
	v_add_f32_e32 v56, 1.0, v56
	v_rcp_f32_e32 v56, v56
	v_add_f32_e32 v57, 1.0, v57
	v_rcp_f32_e32 v57, v57
	v_add_f32_e32 v58, 1.0, v58
	v_rcp_f32_e32 v58, v58
	v_add_f32_e32 v59, 1.0, v59
	v_rcp_f32_e32 v59, v59
	v_mul_f32_e32 v52, 0xbfb8aa3b, v52
	v_exp_f32_e32 v52, v52
	v_mul_f32_e32 v53, 0xbfb8aa3b, v53
	v_exp_f32_e32 v53, v53
	v_mul_f32_e32 v54, 0xbfb8aa3b, v54
	v_exp_f32_e32 v54, v54
	v_mul_f32_e32 v55, 0xbfb8aa3b, v55
	v_exp_f32_e32 v55, v55
	v_add_f32_e32 v52, 1.0, v52
	v_rcp_f32_e32 v52, v52
	v_add_f32_e32 v53, 1.0, v53
	v_rcp_f32_e32 v53, v53
	v_add_f32_e32 v54, 1.0, v54
	v_rcp_f32_e32 v54, v54
	v_add_f32_e32 v55, 1.0, v55
	v_rcp_f32_e32 v55, v55
	v_mul_f32_e32 v48, 0xbfb8aa3b, v48
	v_exp_f32_e32 v48, v48
	v_mul_f32_e32 v49, 0xbfb8aa3b, v49
	v_exp_f32_e32 v49, v49
	v_mul_f32_e32 v50, 0xbfb8aa3b, v50
	v_exp_f32_e32 v50, v50
	v_mul_f32_e32 v51, 0xbfb8aa3b, v51
	v_exp_f32_e32 v51, v51
	v_add_f32_e32 v48, 1.0, v48
	v_rcp_f32_e32 v48, v48
	v_add_f32_e32 v49, 1.0, v49
	v_rcp_f32_e32 v49, v49
	v_add_f32_e32 v50, 1.0, v50
	v_rcp_f32_e32 v50, v50
	v_add_f32_e32 v51, 1.0, v51
	v_rcp_f32_e32 v51, v51
	s_waitcnt vmcnt(7)
	v_lshlrev_b32_e32 v72, 16, v70
	s_waitcnt vmcnt(6)
	v_lshlrev_b32_e32 v73, 16, v66
	v_fmac_f32_e32 v72, v60, v73
	v_and_b32_e32 v60, 0xffff0000, v70
	v_and_b32_e32 v66, 0xffff0000, v66
	v_fmac_f32_e32 v60, v61, v66
	v_lshlrev_b32_e32 v61, 16, v71
	v_lshlrev_b32_e32 v66, 16, v67
	v_fmac_f32_e32 v61, v62, v66
	v_and_b32_e32 v62, 0xffff0000, v71
	v_and_b32_e32 v66, 0xffff0000, v67
	v_fmac_f32_e32 v62, v63, v66
	v_cvt_pk_bf16_f32 v60, v72, v60
	v_cvt_pk_bf16_f32 v61, v61, v62
	global_store_dwordx2 v[68:69], v[60:61], off
	v_lshlrev_b32_e32 v62, 16, v60
	v_and_b32_e32 v60, 0xffff0000, v60
	v_lshlrev_b32_e32 v63, 16, v61
	v_and_b32_e32 v61, 0xffff0000, v61
	v_mul_f32_e32 v60, v60, v60
	v_mul_f32_e32 v61, v61, v61
	v_fmac_f32_e32 v60, v62, v62
	v_fmac_f32_e32 v61, v63, v63
	v_add_f32_e32 v68, v60, v61
	v_lshl_add_u64 v[60:61], v[64:65], 0, s[0:1]
	v_lshl_add_u64 v[62:63], s[26:27], 0, v[60:61]
	v_lshl_add_u64 v[60:61], s[28:29], 0, v[60:61]
	s_mov_b64 s[0:1], 0x40100
	s_waitcnt vmcnt(5)
	v_mov_b32_e32 v66, v186
	v_mov_b32_e32 v67, v187
	v_mov_b32_e32 v60, v188
	v_mov_b32_e32 v61, v189
	v_lshlrev_b32_e32 v69, 16, v66
	v_lshlrev_b32_e32 v70, 16, v60
	v_fmac_f32_e32 v69, v56, v70
	v_and_b32_e32 v56, 0xffff0000, v66
	v_and_b32_e32 v60, 0xffff0000, v60
	v_fmac_f32_e32 v56, v57, v60
	v_lshlrev_b32_e32 v57, 16, v67
	v_lshlrev_b32_e32 v60, 16, v61
	v_fmac_f32_e32 v57, v58, v60
	v_and_b32_e32 v58, 0xffff0000, v67
	v_and_b32_e32 v60, 0xffff0000, v61
	v_fmac_f32_e32 v58, v59, v60
	v_cvt_pk_bf16_f32 v56, v69, v56
	v_cvt_pk_bf16_f32 v57, v57, v58
	global_store_dwordx2 v[62:63], v[56:57], off
	v_lshlrev_b32_e32 v58, 16, v56
	v_and_b32_e32 v56, 0xffff0000, v56
	v_lshlrev_b32_e32 v59, 16, v57
	v_and_b32_e32 v57, 0xffff0000, v57
	v_mul_f32_e32 v56, v56, v56
	v_mul_f32_e32 v57, v57, v57
	v_fmac_f32_e32 v56, v58, v58
	v_fmac_f32_e32 v57, v59, v59
	v_add_f32_e32 v56, v56, v57
	v_add_f32_e32 v62, v68, v56
	v_lshl_add_u64 v[56:57], v[64:65], 0, s[0:1]
	v_lshl_add_u64 v[58:59], s[26:27], 0, v[56:57]
	v_lshl_add_u64 v[56:57], s[28:29], 0, v[56:57]
	s_mov_b64 s[0:1], 0x40120
	s_waitcnt vmcnt(4)
	v_mov_b32_e32 v60, v190
	v_mov_b32_e32 v61, v191
	v_mov_b32_e32 v56, v192
	v_mov_b32_e32 v57, v193
	v_lshlrev_b32_e32 v63, 16, v60
	v_lshlrev_b32_e32 v66, 16, v56
	v_fmac_f32_e32 v63, v52, v66
	v_and_b32_e32 v52, 0xffff0000, v60
	v_and_b32_e32 v56, 0xffff0000, v56
	v_fmac_f32_e32 v52, v53, v56
	v_lshlrev_b32_e32 v53, 16, v61
	v_lshlrev_b32_e32 v56, 16, v57
	v_fmac_f32_e32 v53, v54, v56
	v_and_b32_e32 v54, 0xffff0000, v61
	v_and_b32_e32 v56, 0xffff0000, v57
	v_fmac_f32_e32 v54, v55, v56
	v_cvt_pk_bf16_f32 v52, v63, v52
	v_cvt_pk_bf16_f32 v53, v53, v54
	global_store_dwordx2 v[58:59], v[52:53], off
	v_lshlrev_b32_e32 v54, 16, v52
	v_and_b32_e32 v52, 0xffff0000, v52
	v_lshlrev_b32_e32 v55, 16, v53
	v_and_b32_e32 v53, 0xffff0000, v53
	v_mul_f32_e32 v52, v52, v52
	v_mul_f32_e32 v53, v53, v53
	v_fmac_f32_e32 v52, v54, v54
	v_fmac_f32_e32 v53, v55, v55
	v_add_f32_e32 v52, v52, v53
	v_lshl_add_u64 v[56:57], v[64:65], 0, s[0:1]
	v_add_f32_e32 v54, v62, v52
	v_lshl_add_u64 v[52:53], s[26:27], 0, v[56:57]
	v_lshl_add_u64 v[56:57], s[28:29], 0, v[56:57]
	s_nop 0
	s_waitcnt vmcnt(3)
	v_mov_b32_e32 v58, v194
	v_mov_b32_e32 v59, v195
	v_mov_b32_e32 v56, v196
	v_mov_b32_e32 v57, v197
	v_lshlrev_b32_e32 v55, 16, v58
	v_lshlrev_b32_e32 v60, 16, v56
	v_fmac_f32_e32 v55, v48, v60
	v_and_b32_e32 v48, 0xffff0000, v58
	v_and_b32_e32 v56, 0xffff0000, v56
	v_fmac_f32_e32 v48, v49, v56
	v_lshlrev_b32_e32 v49, 16, v59
	v_lshlrev_b32_e32 v56, 16, v57
	v_fmac_f32_e32 v49, v50, v56
	v_and_b32_e32 v50, 0xffff0000, v59
	v_and_b32_e32 v56, 0xffff0000, v57
	v_fmac_f32_e32 v50, v51, v56
	v_cvt_pk_bf16_f32 v48, v55, v48
	v_cvt_pk_bf16_f32 v49, v49, v50
	global_store_dwordx2 v[52:53], v[48:49], off
	v_lshlrev_b32_e32 v50, 16, v48
	v_and_b32_e32 v48, 0xffff0000, v48
	v_lshlrev_b32_e32 v51, 16, v49
	v_and_b32_e32 v49, 0xffff0000, v49
	v_mul_f32_e32 v48, v48, v48
	v_mul_f32_e32 v49, v49, v49
	v_fmac_f32_e32 v48, v50, v50
	v_fmac_f32_e32 v49, v51, v51
	v_add_f32_e32 v48, v48, v49
	v_add_f32_e32 v48, v54, v48
	ds_bpermute_b32 v49, v116, v48
	s_waitcnt lgkmcnt(0)
	v_add_f32_e32 v48, v48, v49
	ds_bpermute_b32 v49, v117, v48
	s_and_saveexec_b64 s[0:1], s[4:5]
	s_cbranch_execz .LBB0_813
	s_waitcnt lgkmcnt(0)
	v_add_f32_e32 v48, v48, v49
	ds_write_b32 v146, v48 offset:2048
.LBB0_813:
	s_or_b64 exec, exec, s[0:1]
	s_mov_b64 s[0:1], 0x48000
	v_readlane_b32 s26, v251, 20
	v_readlane_b32 s28, v251, 24
	s_waitcnt lgkmcnt(0)
	v_lshl_add_u64 v[48:49], v[64:65], 0, s[0:1]
	v_readlane_b32 s27, v251, 21
	v_readlane_b32 s29, v251, 25
	v_mul_f32_e32 v44, 0xbfb8aa3b, v44
	v_lshl_add_u64 v[50:51], s[26:27], 0, v[48:49]
	v_lshl_add_u64 v[48:49], s[28:29], 0, v[48:49]
	global_load_dwordx2 v[52:53], v[50:51], off
	v_exp_f32_e32 v44, v44
	global_load_dwordx2 v[48:49], v[48:49], off
	s_mov_b64 s[100:101], 0x48020
	v_lshl_add_u64 v[182:183], v[176:177], 0, s[100:101]
	v_lshl_add_u64 v[184:185], v[178:179], 0, v[182:183]
	global_load_dwordx2 v[186:187], v[184:185], off
	v_lshl_add_u64 v[184:185], v[180:181], 0, v[182:183]
	global_load_dwordx2 v[188:189], v[184:185], off
	s_mov_b64 s[100:101], 0x48100
	v_lshl_add_u64 v[182:183], v[176:177], 0, s[100:101]
	v_lshl_add_u64 v[184:185], v[178:179], 0, v[182:183]
	global_load_dwordx2 v[190:191], v[184:185], off
	v_lshl_add_u64 v[184:185], v[180:181], 0, v[182:183]
	global_load_dwordx2 v[192:193], v[184:185], off
	s_mov_b64 s[100:101], 0x48120
	v_lshl_add_u64 v[182:183], v[176:177], 0, s[100:101]
	v_lshl_add_u64 v[184:185], v[178:179], 0, v[182:183]
	global_load_dwordx2 v[194:195], v[184:185], off
	v_lshl_add_u64 v[184:185], v[180:181], 0, v[182:183]
	global_load_dwordx2 v[196:197], v[184:185], off
	v_mul_f32_e32 v45, 0xbfb8aa3b, v45
	v_exp_f32_e32 v45, v45
	v_mul_f32_e32 v46, 0xbfb8aa3b, v46
	v_exp_f32_e32 v46, v46
	v_mul_f32_e32 v47, 0xbfb8aa3b, v47
	v_exp_f32_e32 v47, v47
	v_add_f32_e32 v44, 1.0, v44
	v_rcp_f32_e32 v44, v44
	v_add_f32_e32 v45, 1.0, v45
	v_rcp_f32_e32 v45, v45
	v_add_f32_e32 v46, 1.0, v46
	v_rcp_f32_e32 v46, v46
	v_add_f32_e32 v47, 1.0, v47
	v_rcp_f32_e32 v47, v47
	s_mov_b64 s[0:1], 0x48020
	v_mul_f32_e32 v40, 0xbfb8aa3b, v40
	v_exp_f32_e32 v40, v40
	v_mul_f32_e32 v41, 0xbfb8aa3b, v41
	v_exp_f32_e32 v41, v41
	v_mul_f32_e32 v42, 0xbfb8aa3b, v42
	v_exp_f32_e32 v42, v42
	v_mul_f32_e32 v43, 0xbfb8aa3b, v43
	v_exp_f32_e32 v43, v43
	v_add_f32_e32 v40, 1.0, v40
	v_rcp_f32_e32 v40, v40
	v_add_f32_e32 v41, 1.0, v41
	v_rcp_f32_e32 v41, v41
	v_add_f32_e32 v42, 1.0, v42
	v_rcp_f32_e32 v42, v42
	v_add_f32_e32 v43, 1.0, v43
	v_rcp_f32_e32 v43, v43
	v_mul_f32_e32 v36, 0xbfb8aa3b, v36
	v_exp_f32_e32 v36, v36
	v_mul_f32_e32 v37, 0xbfb8aa3b, v37
	v_exp_f32_e32 v37, v37
	v_mul_f32_e32 v38, 0xbfb8aa3b, v38
	v_exp_f32_e32 v38, v38
	v_mul_f32_e32 v39, 0xbfb8aa3b, v39
	v_exp_f32_e32 v39, v39
	v_add_f32_e32 v36, 1.0, v36
	v_rcp_f32_e32 v36, v36
	v_add_f32_e32 v37, 1.0, v37
	v_rcp_f32_e32 v37, v37
	v_add_f32_e32 v38, 1.0, v38
	v_rcp_f32_e32 v38, v38
	v_add_f32_e32 v39, 1.0, v39
	v_rcp_f32_e32 v39, v39
	v_mul_f32_e32 v32, 0xbfb8aa3b, v32
	v_exp_f32_e32 v32, v32
	v_mul_f32_e32 v33, 0xbfb8aa3b, v33
	v_exp_f32_e32 v33, v33
	v_mul_f32_e32 v34, 0xbfb8aa3b, v34
	v_exp_f32_e32 v34, v34
	v_mul_f32_e32 v35, 0xbfb8aa3b, v35
	v_exp_f32_e32 v35, v35
	v_add_f32_e32 v32, 1.0, v32
	v_rcp_f32_e32 v32, v32
	v_add_f32_e32 v33, 1.0, v33
	v_rcp_f32_e32 v33, v33
	v_add_f32_e32 v34, 1.0, v34
	v_rcp_f32_e32 v34, v34
	v_add_f32_e32 v35, 1.0, v35
	v_rcp_f32_e32 v35, v35
	s_waitcnt vmcnt(7)
	v_lshlrev_b32_e32 v54, 16, v52
	s_waitcnt vmcnt(6)
	v_lshlrev_b32_e32 v55, 16, v48
	v_fmac_f32_e32 v54, v44, v55
	v_and_b32_e32 v44, 0xffff0000, v52
	v_and_b32_e32 v48, 0xffff0000, v48
	v_fmac_f32_e32 v44, v45, v48
	v_lshlrev_b32_e32 v45, 16, v53
	v_lshlrev_b32_e32 v48, 16, v49
	v_fmac_f32_e32 v45, v46, v48
	v_and_b32_e32 v46, 0xffff0000, v53
	v_and_b32_e32 v48, 0xffff0000, v49
	v_fmac_f32_e32 v46, v47, v48
	v_cvt_pk_bf16_f32 v44, v54, v44
	v_cvt_pk_bf16_f32 v45, v45, v46
	global_store_dwordx2 v[50:51], v[44:45], off
	v_lshlrev_b32_e32 v46, 16, v44
	v_and_b32_e32 v44, 0xffff0000, v44
	v_lshlrev_b32_e32 v47, 16, v45
	v_and_b32_e32 v45, 0xffff0000, v45
	v_mul_f32_e32 v44, v44, v44
	v_mul_f32_e32 v45, v45, v45
	v_fmac_f32_e32 v44, v46, v46
	v_fmac_f32_e32 v45, v47, v47
	v_add_f32_e32 v50, v44, v45
	v_lshl_add_u64 v[44:45], v[64:65], 0, s[0:1]
	v_lshl_add_u64 v[46:47], s[26:27], 0, v[44:45]
	v_lshl_add_u64 v[44:45], s[28:29], 0, v[44:45]
	s_mov_b64 s[0:1], 0x48100
	s_waitcnt vmcnt(5)
	v_mov_b32_e32 v48, v186
	v_mov_b32_e32 v49, v187
	v_mov_b32_e32 v44, v188
	v_mov_b32_e32 v45, v189
	v_lshlrev_b32_e32 v51, 16, v48
	v_lshlrev_b32_e32 v52, 16, v44
	v_fmac_f32_e32 v51, v40, v52
	v_and_b32_e32 v40, 0xffff0000, v48
	v_and_b32_e32 v44, 0xffff0000, v44
	v_fmac_f32_e32 v40, v41, v44
	v_lshlrev_b32_e32 v41, 16, v49
	v_lshlrev_b32_e32 v44, 16, v45
	v_fmac_f32_e32 v41, v42, v44
	v_and_b32_e32 v42, 0xffff0000, v49
	v_and_b32_e32 v44, 0xffff0000, v45
	v_fmac_f32_e32 v42, v43, v44
	v_cvt_pk_bf16_f32 v40, v51, v40
	v_cvt_pk_bf16_f32 v41, v41, v42
	global_store_dwordx2 v[46:47], v[40:41], off
	v_lshlrev_b32_e32 v42, 16, v40
	v_and_b32_e32 v40, 0xffff0000, v40
	v_lshlrev_b32_e32 v43, 16, v41
	v_and_b32_e32 v41, 0xffff0000, v41
	v_mul_f32_e32 v40, v40, v40
	v_mul_f32_e32 v41, v41, v41
	v_fmac_f32_e32 v40, v42, v42
	v_fmac_f32_e32 v41, v43, v43
	v_add_f32_e32 v40, v40, v41
	v_add_f32_e32 v46, v50, v40
	v_lshl_add_u64 v[40:41], v[64:65], 0, s[0:1]
	v_lshl_add_u64 v[42:43], s[26:27], 0, v[40:41]
	v_lshl_add_u64 v[40:41], s[28:29], 0, v[40:41]
	s_mov_b64 s[0:1], 0x48120
	s_waitcnt vmcnt(4)
	v_mov_b32_e32 v44, v190
	v_mov_b32_e32 v45, v191
	v_mov_b32_e32 v40, v192
	v_mov_b32_e32 v41, v193
	v_lshlrev_b32_e32 v47, 16, v44
	v_lshlrev_b32_e32 v48, 16, v40
	v_fmac_f32_e32 v47, v36, v48
	v_and_b32_e32 v36, 0xffff0000, v44
	v_and_b32_e32 v40, 0xffff0000, v40
	v_fmac_f32_e32 v36, v37, v40
	v_lshlrev_b32_e32 v37, 16, v45
	v_lshlrev_b32_e32 v40, 16, v41
	v_fmac_f32_e32 v37, v38, v40
	v_and_b32_e32 v38, 0xffff0000, v45
	v_and_b32_e32 v40, 0xffff0000, v41
	v_fmac_f32_e32 v38, v39, v40
	v_cvt_pk_bf16_f32 v36, v47, v36
	v_cvt_pk_bf16_f32 v37, v37, v38
	global_store_dwordx2 v[42:43], v[36:37], off
	v_lshlrev_b32_e32 v38, 16, v36
	v_and_b32_e32 v36, 0xffff0000, v36
	v_lshlrev_b32_e32 v39, 16, v37
	v_and_b32_e32 v37, 0xffff0000, v37
	v_mul_f32_e32 v36, v36, v36
	v_mul_f32_e32 v37, v37, v37
	v_fmac_f32_e32 v36, v38, v38
	v_fmac_f32_e32 v37, v39, v39
	v_add_f32_e32 v36, v36, v37
	v_lshl_add_u64 v[40:41], v[64:65], 0, s[0:1]
	v_add_f32_e32 v38, v46, v36
	v_lshl_add_u64 v[36:37], s[26:27], 0, v[40:41]
	v_lshl_add_u64 v[40:41], s[28:29], 0, v[40:41]
	s_nop 0
	s_waitcnt vmcnt(3)
	v_mov_b32_e32 v42, v194
	v_mov_b32_e32 v43, v195
	v_mov_b32_e32 v40, v196
	v_mov_b32_e32 v41, v197
	v_lshlrev_b32_e32 v39, 16, v42
	v_lshlrev_b32_e32 v44, 16, v40
	v_fmac_f32_e32 v39, v32, v44
	v_and_b32_e32 v32, 0xffff0000, v42
	v_and_b32_e32 v40, 0xffff0000, v40
	v_fmac_f32_e32 v32, v33, v40
	v_lshlrev_b32_e32 v33, 16, v43
	v_lshlrev_b32_e32 v40, 16, v41
	v_fmac_f32_e32 v33, v34, v40
	v_and_b32_e32 v34, 0xffff0000, v43
	v_and_b32_e32 v40, 0xffff0000, v41
	v_fmac_f32_e32 v34, v35, v40
	v_cvt_pk_bf16_f32 v32, v39, v32
	v_cvt_pk_bf16_f32 v33, v33, v34
	global_store_dwordx2 v[36:37], v[32:33], off
	v_lshlrev_b32_e32 v34, 16, v32
	v_and_b32_e32 v32, 0xffff0000, v32
	v_lshlrev_b32_e32 v35, 16, v33
	v_and_b32_e32 v33, 0xffff0000, v33
	v_mul_f32_e32 v32, v32, v32
	v_mul_f32_e32 v33, v33, v33
	v_fmac_f32_e32 v32, v34, v34
	v_fmac_f32_e32 v33, v35, v35
	v_add_f32_e32 v32, v32, v33
	v_add_f32_e32 v32, v38, v32
	ds_bpermute_b32 v33, v116, v32
	s_waitcnt lgkmcnt(0)
	v_add_f32_e32 v32, v32, v33
	ds_bpermute_b32 v33, v117, v32
	s_and_saveexec_b64 s[0:1], s[4:5]
	s_cbranch_execz .LBB0_815
	s_waitcnt lgkmcnt(0)
	v_add_f32_e32 v32, v32, v33
	ds_write_b32 v146, v32 offset:2304
.LBB0_815:
	s_or_b64 exec, exec, s[0:1]
	s_waitcnt lgkmcnt(0)
	v_lshlrev_b64 v[32:33], 10, v[138:139]
	v_lshl_add_u64 v[32:33], v[32:33], 0, v[136:137]
	v_lshlrev_b64 v[32:33], 1, v[32:33]
	s_mov_b64 s[0:1], 0x50000
	v_readlane_b32 s26, v251, 20
	v_readlane_b32 s28, v251, 24
	v_lshl_add_u64 v[34:35], v[32:33], 0, s[0:1]
	v_readlane_b32 s27, v251, 21
	v_readlane_b32 s29, v251, 25
	v_mul_f32_e32 v28, 0xbfb8aa3b, v28
	v_lshl_add_u64 v[36:37], s[26:27], 0, v[34:35]
	v_lshl_add_u64 v[34:35], s[28:29], 0, v[34:35]
	global_load_dwordx2 v[38:39], v[36:37], off
	v_exp_f32_e32 v28, v28
	global_load_dwordx2 v[34:35], v[34:35], off
	s_mov_b64 s[100:101], 0x50020
	v_lshl_add_u64 v[182:183], v[176:177], 0, s[100:101]
	v_lshl_add_u64 v[184:185], v[178:179], 0, v[182:183]
	global_load_dwordx2 v[186:187], v[184:185], off
	v_lshl_add_u64 v[184:185], v[180:181], 0, v[182:183]
	global_load_dwordx2 v[188:189], v[184:185], off
	s_mov_b64 s[100:101], 0x50100
	v_lshl_add_u64 v[182:183], v[176:177], 0, s[100:101]
	v_lshl_add_u64 v[184:185], v[178:179], 0, v[182:183]
	global_load_dwordx2 v[190:191], v[184:185], off
	v_lshl_add_u64 v[184:185], v[180:181], 0, v[182:183]
	global_load_dwordx2 v[192:193], v[184:185], off
	s_mov_b64 s[100:101], 0x50120
	v_lshl_add_u64 v[182:183], v[176:177], 0, s[100:101]
	v_lshl_add_u64 v[184:185], v[178:179], 0, v[182:183]
	global_load_dwordx2 v[194:195], v[184:185], off
	v_lshl_add_u64 v[184:185], v[180:181], 0, v[182:183]
	global_load_dwordx2 v[196:197], v[184:185], off
	v_mul_f32_e32 v29, 0xbfb8aa3b, v29
	v_exp_f32_e32 v29, v29
	v_mul_f32_e32 v30, 0xbfb8aa3b, v30
	v_exp_f32_e32 v30, v30
	v_mul_f32_e32 v31, 0xbfb8aa3b, v31
	v_exp_f32_e32 v31, v31
	v_add_f32_e32 v28, 1.0, v28
	v_rcp_f32_e32 v28, v28
	v_add_f32_e32 v29, 1.0, v29
	v_rcp_f32_e32 v29, v29
	v_add_f32_e32 v30, 1.0, v30
	v_rcp_f32_e32 v30, v30
	v_add_f32_e32 v31, 1.0, v31
	v_rcp_f32_e32 v31, v31
	s_mov_b64 s[0:1], 0x50020
	v_mul_f32_e32 v24, 0xbfb8aa3b, v24
	v_exp_f32_e32 v24, v24
	v_mul_f32_e32 v25, 0xbfb8aa3b, v25
	v_exp_f32_e32 v25, v25
	v_mul_f32_e32 v26, 0xbfb8aa3b, v26
	v_exp_f32_e32 v26, v26
	v_mul_f32_e32 v27, 0xbfb8aa3b, v27
	v_exp_f32_e32 v27, v27
	v_add_f32_e32 v24, 1.0, v24
	v_rcp_f32_e32 v24, v24
	v_add_f32_e32 v25, 1.0, v25
	v_rcp_f32_e32 v25, v25
	v_add_f32_e32 v26, 1.0, v26
	v_rcp_f32_e32 v26, v26
	v_add_f32_e32 v27, 1.0, v27
	v_rcp_f32_e32 v27, v27
	v_mul_f32_e32 v20, 0xbfb8aa3b, v20
	v_exp_f32_e32 v20, v20
	v_mul_f32_e32 v21, 0xbfb8aa3b, v21
	v_exp_f32_e32 v21, v21
	v_mul_f32_e32 v22, 0xbfb8aa3b, v22
	v_exp_f32_e32 v22, v22
	v_mul_f32_e32 v23, 0xbfb8aa3b, v23
	v_exp_f32_e32 v23, v23
	v_add_f32_e32 v20, 1.0, v20
	v_rcp_f32_e32 v20, v20
	v_add_f32_e32 v21, 1.0, v21
	v_rcp_f32_e32 v21, v21
	v_add_f32_e32 v22, 1.0, v22
	v_rcp_f32_e32 v22, v22
	v_add_f32_e32 v23, 1.0, v23
	v_rcp_f32_e32 v23, v23
	v_mul_f32_e32 v16, 0xbfb8aa3b, v16
	v_exp_f32_e32 v16, v16
	v_mul_f32_e32 v17, 0xbfb8aa3b, v17
	v_exp_f32_e32 v17, v17
	v_mul_f32_e32 v18, 0xbfb8aa3b, v18
	v_exp_f32_e32 v18, v18
	v_mul_f32_e32 v19, 0xbfb8aa3b, v19
	v_exp_f32_e32 v19, v19
	v_add_f32_e32 v16, 1.0, v16
	v_rcp_f32_e32 v16, v16
	v_add_f32_e32 v17, 1.0, v17
	v_rcp_f32_e32 v17, v17
	v_add_f32_e32 v18, 1.0, v18
	v_rcp_f32_e32 v18, v18
	v_add_f32_e32 v19, 1.0, v19
	v_rcp_f32_e32 v19, v19
	s_waitcnt vmcnt(7)
	v_lshlrev_b32_e32 v40, 16, v38
	s_waitcnt vmcnt(6)
	v_lshlrev_b32_e32 v41, 16, v34
	v_fmac_f32_e32 v40, v28, v41
	v_and_b32_e32 v28, 0xffff0000, v38
	v_and_b32_e32 v34, 0xffff0000, v34
	v_fmac_f32_e32 v28, v29, v34
	v_lshlrev_b32_e32 v29, 16, v39
	v_lshlrev_b32_e32 v34, 16, v35
	v_fmac_f32_e32 v29, v30, v34
	v_and_b32_e32 v30, 0xffff0000, v39
	v_and_b32_e32 v34, 0xffff0000, v35
	v_fmac_f32_e32 v30, v31, v34
	v_cvt_pk_bf16_f32 v28, v40, v28
	v_cvt_pk_bf16_f32 v29, v29, v30
	global_store_dwordx2 v[36:37], v[28:29], off
	v_lshlrev_b32_e32 v30, 16, v28
	v_and_b32_e32 v28, 0xffff0000, v28
	v_lshlrev_b32_e32 v31, 16, v29
	v_and_b32_e32 v29, 0xffff0000, v29
	v_mul_f32_e32 v28, v28, v28
	v_mul_f32_e32 v29, v29, v29
	v_fmac_f32_e32 v28, v30, v30
	v_fmac_f32_e32 v29, v31, v31
	v_add_f32_e32 v36, v28, v29
	v_lshl_add_u64 v[28:29], v[32:33], 0, s[0:1]
	v_lshl_add_u64 v[30:31], s[26:27], 0, v[28:29]
	v_lshl_add_u64 v[28:29], s[28:29], 0, v[28:29]
	s_mov_b64 s[0:1], 0x50100
	s_waitcnt vmcnt(5)
	v_mov_b32_e32 v34, v186
	v_mov_b32_e32 v35, v187
	v_mov_b32_e32 v28, v188
	v_mov_b32_e32 v29, v189
	v_lshlrev_b32_e32 v37, 16, v34
	v_lshlrev_b32_e32 v38, 16, v28
	v_fmac_f32_e32 v37, v24, v38
	v_and_b32_e32 v24, 0xffff0000, v34
	v_and_b32_e32 v28, 0xffff0000, v28
	v_fmac_f32_e32 v24, v25, v28
	v_lshlrev_b32_e32 v25, 16, v35
	v_lshlrev_b32_e32 v28, 16, v29
	v_fmac_f32_e32 v25, v26, v28
	v_and_b32_e32 v26, 0xffff0000, v35
	v_and_b32_e32 v28, 0xffff0000, v29
	v_fmac_f32_e32 v26, v27, v28
	v_cvt_pk_bf16_f32 v24, v37, v24
	v_cvt_pk_bf16_f32 v25, v25, v26
	global_store_dwordx2 v[30:31], v[24:25], off
	v_lshlrev_b32_e32 v26, 16, v24
	v_and_b32_e32 v24, 0xffff0000, v24
	v_lshlrev_b32_e32 v27, 16, v25
	v_and_b32_e32 v25, 0xffff0000, v25
	v_mul_f32_e32 v24, v24, v24
	v_mul_f32_e32 v25, v25, v25
	v_fmac_f32_e32 v24, v26, v26
	v_fmac_f32_e32 v25, v27, v27
	v_add_f32_e32 v24, v24, v25
	v_add_f32_e32 v30, v36, v24
	v_lshl_add_u64 v[24:25], v[32:33], 0, s[0:1]
	v_lshl_add_u64 v[26:27], s[26:27], 0, v[24:25]
	v_lshl_add_u64 v[24:25], s[28:29], 0, v[24:25]
	s_mov_b64 s[0:1], 0x50120
	s_waitcnt vmcnt(4)
	v_mov_b32_e32 v28, v190
	v_mov_b32_e32 v29, v191
	v_mov_b32_e32 v24, v192
	v_mov_b32_e32 v25, v193
	v_lshlrev_b32_e32 v31, 16, v28
	v_lshlrev_b32_e32 v34, 16, v24
	v_fmac_f32_e32 v31, v20, v34
	v_and_b32_e32 v20, 0xffff0000, v28
	v_and_b32_e32 v24, 0xffff0000, v24
	v_fmac_f32_e32 v20, v21, v24
	v_lshlrev_b32_e32 v21, 16, v29
	v_lshlrev_b32_e32 v24, 16, v25
	v_fmac_f32_e32 v21, v22, v24
	v_and_b32_e32 v22, 0xffff0000, v29
	v_and_b32_e32 v24, 0xffff0000, v25
	v_fmac_f32_e32 v22, v23, v24
	v_cvt_pk_bf16_f32 v20, v31, v20
	v_cvt_pk_bf16_f32 v21, v21, v22
	global_store_dwordx2 v[26:27], v[20:21], off
	v_lshlrev_b32_e32 v22, 16, v20
	v_and_b32_e32 v20, 0xffff0000, v20
	v_lshlrev_b32_e32 v23, 16, v21
	v_and_b32_e32 v21, 0xffff0000, v21
	v_mul_f32_e32 v20, v20, v20
	v_mul_f32_e32 v21, v21, v21
	v_fmac_f32_e32 v20, v22, v22
	v_fmac_f32_e32 v21, v23, v23
	v_add_f32_e32 v20, v20, v21
	v_lshl_add_u64 v[24:25], v[32:33], 0, s[0:1]
	v_add_f32_e32 v22, v30, v20
	v_lshl_add_u64 v[20:21], s[26:27], 0, v[24:25]
	v_lshl_add_u64 v[24:25], s[28:29], 0, v[24:25]
	s_nop 0
	s_waitcnt vmcnt(3)
	v_mov_b32_e32 v26, v194
	v_mov_b32_e32 v27, v195
	v_mov_b32_e32 v24, v196
	v_mov_b32_e32 v25, v197
	v_lshlrev_b32_e32 v23, 16, v26
	v_lshlrev_b32_e32 v28, 16, v24
	v_fmac_f32_e32 v23, v16, v28
	v_and_b32_e32 v16, 0xffff0000, v26
	v_and_b32_e32 v24, 0xffff0000, v24
	v_fmac_f32_e32 v16, v17, v24
	v_lshlrev_b32_e32 v17, 16, v27
	v_lshlrev_b32_e32 v24, 16, v25
	v_fmac_f32_e32 v17, v18, v24
	v_and_b32_e32 v18, 0xffff0000, v27
	v_and_b32_e32 v24, 0xffff0000, v25
	v_fmac_f32_e32 v18, v19, v24
	v_cvt_pk_bf16_f32 v16, v23, v16
	v_cvt_pk_bf16_f32 v17, v17, v18
	global_store_dwordx2 v[20:21], v[16:17], off
	v_lshlrev_b32_e32 v18, 16, v16
	v_and_b32_e32 v16, 0xffff0000, v16
	v_lshlrev_b32_e32 v19, 16, v17
	v_and_b32_e32 v17, 0xffff0000, v17
	v_mul_f32_e32 v16, v16, v16
	v_mul_f32_e32 v17, v17, v17
	v_fmac_f32_e32 v16, v18, v18
	v_fmac_f32_e32 v17, v19, v19
	v_add_f32_e32 v16, v16, v17
	v_add_f32_e32 v16, v22, v16
	ds_bpermute_b32 v17, v116, v16
	s_waitcnt lgkmcnt(0)
	v_add_f32_e32 v16, v16, v17
	ds_bpermute_b32 v17, v117, v16
	s_and_saveexec_b64 s[0:1], s[4:5]
	s_cbranch_execz .LBB0_817
	s_waitcnt lgkmcnt(0)
	v_add_f32_e32 v16, v16, v17
	ds_write_b32 v146, v16 offset:2560
.LBB0_817:
	s_or_b64 exec, exec, s[0:1]
	s_mov_b64 s[0:1], 0x58000
	v_readlane_b32 s26, v251, 20
	v_readlane_b32 s28, v251, 24
	s_waitcnt lgkmcnt(0)
	v_lshl_add_u64 v[16:17], v[32:33], 0, s[0:1]
	v_readlane_b32 s27, v251, 21
	v_readlane_b32 s29, v251, 25
	v_mul_f32_e32 v12, 0xbfb8aa3b, v12
	v_lshl_add_u64 v[18:19], s[26:27], 0, v[16:17]
	v_lshl_add_u64 v[16:17], s[28:29], 0, v[16:17]
	global_load_dwordx2 v[20:21], v[18:19], off
	v_exp_f32_e32 v12, v12
	global_load_dwordx2 v[16:17], v[16:17], off
	s_mov_b64 s[100:101], 0x58020
	v_lshl_add_u64 v[182:183], v[176:177], 0, s[100:101]
	v_lshl_add_u64 v[184:185], v[178:179], 0, v[182:183]
	global_load_dwordx2 v[186:187], v[184:185], off
	v_lshl_add_u64 v[184:185], v[180:181], 0, v[182:183]
	global_load_dwordx2 v[188:189], v[184:185], off
	s_mov_b64 s[100:101], 0x58100
	v_lshl_add_u64 v[182:183], v[176:177], 0, s[100:101]
	v_lshl_add_u64 v[184:185], v[178:179], 0, v[182:183]
	global_load_dwordx2 v[190:191], v[184:185], off
	v_lshl_add_u64 v[184:185], v[180:181], 0, v[182:183]
	global_load_dwordx2 v[192:193], v[184:185], off
	s_mov_b64 s[100:101], 0x58120
	v_lshl_add_u64 v[182:183], v[176:177], 0, s[100:101]
	v_lshl_add_u64 v[184:185], v[178:179], 0, v[182:183]
	global_load_dwordx2 v[194:195], v[184:185], off
	v_lshl_add_u64 v[184:185], v[180:181], 0, v[182:183]
	global_load_dwordx2 v[196:197], v[184:185], off
	v_mul_f32_e32 v13, 0xbfb8aa3b, v13
	v_exp_f32_e32 v13, v13
	v_mul_f32_e32 v14, 0xbfb8aa3b, v14
	v_exp_f32_e32 v14, v14
	v_mul_f32_e32 v15, 0xbfb8aa3b, v15
	v_exp_f32_e32 v15, v15
	v_add_f32_e32 v12, 1.0, v12
	v_rcp_f32_e32 v12, v12
	v_add_f32_e32 v13, 1.0, v13
	v_rcp_f32_e32 v13, v13
	v_add_f32_e32 v14, 1.0, v14
	v_rcp_f32_e32 v14, v14
	v_add_f32_e32 v15, 1.0, v15
	v_rcp_f32_e32 v15, v15
	s_mov_b64 s[0:1], 0x58020
	v_mul_f32_e32 v8, 0xbfb8aa3b, v8
	v_exp_f32_e32 v8, v8
	v_mul_f32_e32 v9, 0xbfb8aa3b, v9
	v_exp_f32_e32 v9, v9
	v_mul_f32_e32 v10, 0xbfb8aa3b, v10
	v_exp_f32_e32 v10, v10
	v_mul_f32_e32 v11, 0xbfb8aa3b, v11
	v_exp_f32_e32 v11, v11
	v_add_f32_e32 v8, 1.0, v8
	v_rcp_f32_e32 v8, v8
	v_add_f32_e32 v9, 1.0, v9
	v_rcp_f32_e32 v9, v9
	v_add_f32_e32 v10, 1.0, v10
	v_rcp_f32_e32 v10, v10
	v_add_f32_e32 v11, 1.0, v11
	v_rcp_f32_e32 v11, v11
	v_mul_f32_e32 v4, 0xbfb8aa3b, v4
	v_exp_f32_e32 v4, v4
	v_mul_f32_e32 v5, 0xbfb8aa3b, v5
	v_exp_f32_e32 v5, v5
	v_mul_f32_e32 v6, 0xbfb8aa3b, v6
	v_exp_f32_e32 v6, v6
	v_mul_f32_e32 v7, 0xbfb8aa3b, v7
	v_exp_f32_e32 v7, v7
	v_add_f32_e32 v4, 1.0, v4
	v_rcp_f32_e32 v4, v4
	v_add_f32_e32 v5, 1.0, v5
	v_rcp_f32_e32 v5, v5
	v_add_f32_e32 v6, 1.0, v6
	v_rcp_f32_e32 v6, v6
	v_add_f32_e32 v7, 1.0, v7
	v_rcp_f32_e32 v7, v7
	v_mul_f32_e32 v0, 0xbfb8aa3b, v0
	v_exp_f32_e32 v0, v0
	v_mul_f32_e32 v1, 0xbfb8aa3b, v1
	v_exp_f32_e32 v1, v1
	v_mul_f32_e32 v2, 0xbfb8aa3b, v2
	v_exp_f32_e32 v2, v2
	v_mul_f32_e32 v3, 0xbfb8aa3b, v3
	v_exp_f32_e32 v3, v3
	v_add_f32_e32 v0, 1.0, v0
	v_rcp_f32_e32 v0, v0
	v_add_f32_e32 v1, 1.0, v1
	v_rcp_f32_e32 v1, v1
	v_add_f32_e32 v2, 1.0, v2
	v_rcp_f32_e32 v2, v2
	v_add_f32_e32 v3, 1.0, v3
	v_rcp_f32_e32 v3, v3
	s_waitcnt vmcnt(7)
	v_lshlrev_b32_e32 v22, 16, v20
	s_waitcnt vmcnt(6)
	v_lshlrev_b32_e32 v23, 16, v16
	v_fmac_f32_e32 v22, v12, v23
	v_and_b32_e32 v12, 0xffff0000, v20
	v_and_b32_e32 v16, 0xffff0000, v16
	v_fmac_f32_e32 v12, v13, v16
	v_lshlrev_b32_e32 v13, 16, v21
	v_lshlrev_b32_e32 v16, 16, v17
	v_fmac_f32_e32 v13, v14, v16
	v_and_b32_e32 v14, 0xffff0000, v21
	v_and_b32_e32 v16, 0xffff0000, v17
	v_fmac_f32_e32 v14, v15, v16
	v_cvt_pk_bf16_f32 v12, v22, v12
	v_cvt_pk_bf16_f32 v13, v13, v14
	global_store_dwordx2 v[18:19], v[12:13], off
	v_lshlrev_b32_e32 v14, 16, v12
	v_and_b32_e32 v12, 0xffff0000, v12
	v_lshlrev_b32_e32 v15, 16, v13
	v_and_b32_e32 v13, 0xffff0000, v13
	v_mul_f32_e32 v12, v12, v12
	v_mul_f32_e32 v13, v13, v13
	v_fmac_f32_e32 v12, v14, v14
	v_fmac_f32_e32 v13, v15, v15
	v_add_f32_e32 v18, v12, v13
	v_lshl_add_u64 v[12:13], v[32:33], 0, s[0:1]
	v_lshl_add_u64 v[14:15], s[26:27], 0, v[12:13]
	v_lshl_add_u64 v[12:13], s[28:29], 0, v[12:13]
	s_mov_b64 s[0:1], 0x58100
	s_waitcnt vmcnt(5)
	v_mov_b32_e32 v16, v186
	v_mov_b32_e32 v17, v187
	v_mov_b32_e32 v12, v188
	v_mov_b32_e32 v13, v189
	v_lshlrev_b32_e32 v19, 16, v16
	v_lshlrev_b32_e32 v20, 16, v12
	v_fmac_f32_e32 v19, v8, v20
	v_and_b32_e32 v8, 0xffff0000, v16
	v_and_b32_e32 v12, 0xffff0000, v12
	v_fmac_f32_e32 v8, v9, v12
	v_lshlrev_b32_e32 v9, 16, v17
	v_lshlrev_b32_e32 v12, 16, v13
	v_fmac_f32_e32 v9, v10, v12
	v_and_b32_e32 v10, 0xffff0000, v17
	v_and_b32_e32 v12, 0xffff0000, v13
	v_fmac_f32_e32 v10, v11, v12
	v_cvt_pk_bf16_f32 v8, v19, v8
	v_cvt_pk_bf16_f32 v9, v9, v10
	global_store_dwordx2 v[14:15], v[8:9], off
	v_lshlrev_b32_e32 v10, 16, v8
	v_and_b32_e32 v8, 0xffff0000, v8
	v_lshlrev_b32_e32 v11, 16, v9
	v_and_b32_e32 v9, 0xffff0000, v9
	v_mul_f32_e32 v8, v8, v8
	v_mul_f32_e32 v9, v9, v9
	v_fmac_f32_e32 v8, v10, v10
	v_fmac_f32_e32 v9, v11, v11
	v_add_f32_e32 v8, v8, v9
	v_add_f32_e32 v14, v18, v8
	v_lshl_add_u64 v[8:9], v[32:33], 0, s[0:1]
	v_lshl_add_u64 v[10:11], s[26:27], 0, v[8:9]
	v_lshl_add_u64 v[8:9], s[28:29], 0, v[8:9]
	s_mov_b64 s[0:1], 0x58120
	s_waitcnt vmcnt(4)
	v_mov_b32_e32 v12, v190
	v_mov_b32_e32 v13, v191
	v_mov_b32_e32 v8, v192
	v_mov_b32_e32 v9, v193
	v_lshlrev_b32_e32 v15, 16, v12
	v_lshlrev_b32_e32 v16, 16, v8
	v_fmac_f32_e32 v15, v4, v16
	v_and_b32_e32 v4, 0xffff0000, v12
	v_and_b32_e32 v8, 0xffff0000, v8
	v_fmac_f32_e32 v4, v5, v8
	v_lshlrev_b32_e32 v5, 16, v13
	v_lshlrev_b32_e32 v8, 16, v9
	v_fmac_f32_e32 v5, v6, v8
	v_and_b32_e32 v6, 0xffff0000, v13
	v_and_b32_e32 v8, 0xffff0000, v9
	v_fmac_f32_e32 v6, v7, v8
	v_cvt_pk_bf16_f32 v4, v15, v4
	v_cvt_pk_bf16_f32 v5, v5, v6
	global_store_dwordx2 v[10:11], v[4:5], off
	v_lshlrev_b32_e32 v6, 16, v4
	v_and_b32_e32 v4, 0xffff0000, v4
	v_lshlrev_b32_e32 v7, 16, v5
	v_and_b32_e32 v5, 0xffff0000, v5
	v_mul_f32_e32 v4, v4, v4
	v_mul_f32_e32 v5, v5, v5
	v_fmac_f32_e32 v4, v6, v6
	v_fmac_f32_e32 v5, v7, v7
	v_add_f32_e32 v4, v4, v5
	v_lshl_add_u64 v[8:9], v[32:33], 0, s[0:1]
	v_add_f32_e32 v6, v14, v4
	v_lshl_add_u64 v[4:5], s[26:27], 0, v[8:9]
	v_lshl_add_u64 v[8:9], s[28:29], 0, v[8:9]
	s_nop 0
	s_waitcnt vmcnt(3)
	v_mov_b32_e32 v10, v194
	v_mov_b32_e32 v11, v195
	v_mov_b32_e32 v8, v196
	v_mov_b32_e32 v9, v197
	v_lshlrev_b32_e32 v7, 16, v10
	v_lshlrev_b32_e32 v12, 16, v8
	v_fmac_f32_e32 v7, v0, v12
	v_and_b32_e32 v0, 0xffff0000, v10
	v_and_b32_e32 v8, 0xffff0000, v8
	v_fmac_f32_e32 v0, v1, v8
	v_lshlrev_b32_e32 v1, 16, v11
	v_lshlrev_b32_e32 v8, 16, v9
	v_fmac_f32_e32 v1, v2, v8
	v_and_b32_e32 v2, 0xffff0000, v11
	v_and_b32_e32 v8, 0xffff0000, v9
	v_fmac_f32_e32 v2, v3, v8
	v_cvt_pk_bf16_f32 v0, v7, v0
	v_cvt_pk_bf16_f32 v1, v1, v2
	global_store_dwordx2 v[4:5], v[0:1], off
	v_lshlrev_b32_e32 v2, 16, v0
	v_and_b32_e32 v0, 0xffff0000, v0
	v_lshlrev_b32_e32 v3, 16, v1
	v_and_b32_e32 v1, 0xffff0000, v1
	v_mul_f32_e32 v0, v0, v0
	v_mul_f32_e32 v1, v1, v1
	v_fmac_f32_e32 v0, v2, v2
	v_fmac_f32_e32 v1, v3, v3
	v_add_f32_e32 v0, v0, v1
	v_add_f32_e32 v0, v6, v0
	ds_bpermute_b32 v1, v116, v0
	s_waitcnt lgkmcnt(0)
	v_add_f32_e32 v0, v0, v1
	ds_bpermute_b32 v1, v117, v0
	s_and_saveexec_b64 s[0:1], s[4:5]
	s_cbranch_execz .LBB0_819
	s_waitcnt lgkmcnt(0)
	v_add_f32_e32 v0, v0, v1
	ds_write_b32 v146, v0 offset:2816
